# A-fragment LDS prefetch deepened to two MFMA groups ahead with a third fragment buffer; waits recounted
# baseline (speedup 1.0000x reference)
; #define MFMA16(a, b, c) __builtin_amdgcn_mfma_f32_16x16x32_bf16((a), (b), (c), 0, 0, 0)
;     ...
;   for (int kt = 0; kt < nk; ++kt) {
;     const int buf = kt & 1;
;     const char* cA = smem + buf * STAGE + (wm * 32 * MI + r16) * 128;
;     const char* cB = smem + buf * STAGE + 32768 + (wn * 64 + r16) * 128;
; #pragma unroll
;     for (int k2 = 0; k2 < 2; ++k2) {
;       if (k2 == 1 && kt + 1 < nk) STAGE_TILE(buf ^ 1, (kt + 1) * 64)
;       const int po = ((4 * k2 + q4) ^ swz) * 16;
;       bf16x8 bf[4];
; #pragma unroll
;       for (int nt = 0; nt < 4; ++nt) bf[nt] = *(const bf16x8*)(cB + nt * 16 * 128 + po);
;       bf16x8 afc = *(const bf16x8*)(cA + po);
; #pragma unroll
;       for (int a = 0; a < MT; ++a) {
;         bf16x8 afn = afc;
;         if (a + 1 < MT) afn = *(const bf16x8*)(cA + (a + 1) * 16 * 128 + po);
;         __builtin_amdgcn_sched_barrier(0);
; #pragma unroll
;         for (int nt = 0; nt < 4; ++nt) acc[a][nt] = MFMA16(bf[nt], afc, acc[a][nt]);
;         __builtin_amdgcn_sched_barrier(0);
;         afc = afn;
;       }
;     }
;     asm volatile("s_waitcnt vmcnt(0)" ::: "memory");
;     __syncthreads();
;   }
.LBB0_48:
	s_and_b32 s42, s41, 0x10000
	s_add_i32 s43, s42, 0
	s_xor_b32 s42, s42, 0x10000
	v_add_u32_e32 v174, s43, v147
	v_add_u32_e32 v162, v174, v146
	v_add_u32_e32 v149, s43, v148
	v_add_u32_e32 v175, v149, v146
	ds_read_b128 v[150:153], v162 offset:32768
	ds_read_b128 v[166:169], v175
	ds_read_b128 v[154:157], v162 offset:34816
	ds_read_b128 v[158:161], v162 offset:36864
	ds_read_b128 v[162:165], v162 offset:38912
	ds_read_b128 v[170:173], v175 offset:2048
	ds_read_b128 v[184:187], v175 offset:4096
	s_waitcnt lgkmcnt(5)
	v_mfma_f32_16x16x32_bf16 v[126:129], v[150:153], v[166:169], v[126:129]
	v_readfirstlane_b32 s43, v145
	s_waitcnt lgkmcnt(4)
	v_mfma_f32_16x16x32_bf16 v[122:125], v[154:157], v[166:169], v[122:125]
	s_nop 0
	s_waitcnt lgkmcnt(3)
	v_mfma_f32_16x16x32_bf16 v[118:121], v[158:161], v[166:169], v[118:121]
	s_add_u32 s43, s43, s42
	s_waitcnt lgkmcnt(2)
	v_mfma_f32_16x16x32_bf16 v[114:117], v[162:165], v[166:169], v[114:117]
	ds_read_b128 v[166:169], v175 offset:6144
	s_waitcnt lgkmcnt(2)
	v_mfma_f32_16x16x32_bf16 v[110:113], v[150:153], v[170:173], v[110:113]
	s_add_u32 m0, s43, 0x0
	v_mfma_f32_16x16x32_bf16 v[106:109], v[154:157], v[170:173], v[106:109]
	global_load_lds_dwordx4 v176, s[100:101]
	v_mfma_f32_16x16x32_bf16 v[102:105], v[158:161], v[170:173], v[102:105]
	s_add_u32 m0, s43, 0x2000
	v_mfma_f32_16x16x32_bf16 v[98:101], v[162:165], v[170:173], v[98:101]
	ds_read_b128 v[170:173], v175 offset:8192
	s_waitcnt lgkmcnt(2)
	v_mfma_f32_16x16x32_bf16 v[94:97], v[150:153], v[184:187], v[94:97]
	global_load_lds_dwordx4 v177, s[100:101]
	v_mfma_f32_16x16x32_bf16 v[90:93], v[154:157], v[184:187], v[90:93]
	s_add_u32 m0, s43, 0x4000
	v_mfma_f32_16x16x32_bf16 v[86:89], v[158:161], v[184:187], v[86:89]
	global_load_lds_dwordx4 v178, s[100:101]
	v_mfma_f32_16x16x32_bf16 v[82:85], v[162:165], v[184:187], v[82:85]
	ds_read_b128 v[184:187], v175 offset:10240
	s_waitcnt lgkmcnt(2)
	v_mfma_f32_16x16x32_bf16 v[78:81], v[150:153], v[166:169], v[78:81]
	s_add_u32 m0, s43, 0x6000
	v_mfma_f32_16x16x32_bf16 v[74:77], v[154:157], v[166:169], v[74:77]
	global_load_lds_dwordx4 v179, s[100:101]
	v_mfma_f32_16x16x32_bf16 v[70:73], v[158:161], v[166:169], v[70:73]
	s_add_u32 m0, s43, 0x8000
	v_mfma_f32_16x16x32_bf16 v[66:69], v[162:165], v[166:169], v[66:69]
	ds_read_b128 v[166:169], v175 offset:12288
	s_waitcnt lgkmcnt(2)
	v_mfma_f32_16x16x32_bf16 v[62:65], v[150:153], v[170:173], v[62:65]
	global_load_lds_dwordx4 v180, s[100:101]
	v_mfma_f32_16x16x32_bf16 v[58:61], v[154:157], v[170:173], v[58:61]
	s_add_u32 m0, s43, 0xa000
	v_mfma_f32_16x16x32_bf16 v[54:57], v[158:161], v[170:173], v[54:57]
	global_load_lds_dwordx4 v181, s[100:101]
	v_mfma_f32_16x16x32_bf16 v[50:53], v[162:165], v[170:173], v[50:53]
	ds_read_b128 v[170:173], v175 offset:14336
	s_waitcnt lgkmcnt(2)
	v_mfma_f32_16x16x32_bf16 v[46:49], v[150:153], v[184:187], v[46:49]
	s_add_u32 m0, s43, 0xc000
	v_mfma_f32_16x16x32_bf16 v[42:45], v[154:157], v[184:187], v[42:45]
	global_load_lds_dwordx4 v182, s[100:101]
	v_mfma_f32_16x16x32_bf16 v[38:41], v[158:161], v[184:187], v[38:41]
	s_add_u32 m0, s43, 0xe000
	v_mfma_f32_16x16x32_bf16 v[34:37], v[162:165], v[184:187], v[34:37]
	s_waitcnt lgkmcnt(1)
	v_mfma_f32_16x16x32_bf16 v[30:33], v[150:153], v[166:169], v[30:33]
	global_load_lds_dwordx4 v183, s[100:101]
	v_mfma_f32_16x16x32_bf16 v[26:29], v[154:157], v[166:169], v[26:29]
	v_mfma_f32_16x16x32_bf16 v[22:25], v[158:161], v[166:169], v[22:25]
	v_mfma_f32_16x16x32_bf16 v[18:21], v[162:165], v[166:169], v[18:21]
	s_waitcnt lgkmcnt(0)
	v_mfma_f32_16x16x32_bf16 v[14:17], v[150:153], v[170:173], v[14:17]
	v_mfma_f32_16x16x32_bf16 v[10:13], v[154:157], v[170:173], v[10:13]
	v_mfma_f32_16x16x32_bf16 v[6:9], v[158:161], v[170:173], v[6:9]
	v_mfma_f32_16x16x32_bf16 v[2:5], v[162:165], v[170:173], v[2:5]
	v_add_u32_e32 v162, v174, v144
	v_add_u32_e32 v149, v149, v144
	ds_read_b128 v[150:153], v162 offset:32768
	ds_read_b128 v[166:169], v149
	ds_read_b128 v[154:157], v162 offset:34816
	ds_read_b128 v[158:161], v162 offset:36864
	ds_read_b128 v[162:165], v162 offset:38912
	ds_read_b128 v[170:173], v149 offset:2048
	ds_read_b128 v[184:187], v149 offset:4096
	s_waitcnt lgkmcnt(5)
	v_mfma_f32_16x16x32_bf16 v[126:129], v[150:153], v[166:169], v[126:129]
	s_add_u32 s100, s100, 0x80
	s_waitcnt lgkmcnt(4)
	v_mfma_f32_16x16x32_bf16 v[122:125], v[154:157], v[166:169], v[122:125]
	s_addc_u32 s101, s101, 0
	s_waitcnt lgkmcnt(3)
	v_mfma_f32_16x16x32_bf16 v[118:121], v[158:161], v[166:169], v[118:121]
	s_add_u32 s16, s16, 0x80
	s_waitcnt lgkmcnt(2)
	v_mfma_f32_16x16x32_bf16 v[114:117], v[162:165], v[166:169], v[114:117]
	ds_read_b128 v[166:169], v149 offset:6144
	s_waitcnt lgkmcnt(2)
	v_mfma_f32_16x16x32_bf16 v[110:113], v[150:153], v[170:173], v[110:113]
	s_addc_u32 s17, s17, 0
	v_mfma_f32_16x16x32_bf16 v[106:109], v[154:157], v[170:173], v[106:109]
	s_add_i32 s41, s41, 0x10000
	v_mfma_f32_16x16x32_bf16 v[102:105], v[158:161], v[170:173], v[102:105]
	v_mfma_f32_16x16x32_bf16 v[98:101], v[162:165], v[170:173], v[98:101]
	ds_read_b128 v[170:173], v149 offset:8192
	s_waitcnt lgkmcnt(2)
	v_mfma_f32_16x16x32_bf16 v[94:97], v[150:153], v[184:187], v[94:97]
	v_mfma_f32_16x16x32_bf16 v[90:93], v[154:157], v[184:187], v[90:93]
	v_mfma_f32_16x16x32_bf16 v[86:89], v[158:161], v[184:187], v[86:89]
	v_mfma_f32_16x16x32_bf16 v[82:85], v[162:165], v[184:187], v[82:85]
	ds_read_b128 v[184:187], v149 offset:10240
	s_waitcnt lgkmcnt(2)
	v_mfma_f32_16x16x32_bf16 v[78:81], v[150:153], v[166:169], v[78:81]
	v_mfma_f32_16x16x32_bf16 v[74:77], v[154:157], v[166:169], v[74:77]
	v_mfma_f32_16x16x32_bf16 v[70:73], v[158:161], v[166:169], v[70:73]
	v_mfma_f32_16x16x32_bf16 v[66:69], v[162:165], v[166:169], v[66:69]
	ds_read_b128 v[166:169], v149 offset:12288
	s_waitcnt lgkmcnt(2)
; #define MFMA16(a, b, c) __builtin_amdgcn_mfma_f32_16x16x32_bf16((a), (b), (c), 0, 0, 0)
;     ...
;   for (int kt = 0; kt < nk; ++kt) {
;     const int buf = kt & 1;
;     const char* cA = smem + buf * STAGE + (wm * 32 * MI + r16) * 128;
;     const char* cB = smem + buf * STAGE + 32768 + (wn * 64 + r16) * 128;
; #pragma unroll
;     for (int k2 = 0; k2 < 2; ++k2) {
;       if (k2 == 1 && kt + 1 < nk) STAGE_TILE(buf ^ 1, (kt + 1) * 64)
;       const int po = ((4 * k2 + q4) ^ swz) * 16;
;       bf16x8 bf[4];
; #pragma unroll
;       for (int nt = 0; nt < 4; ++nt) bf[nt] = *(const bf16x8*)(cB + nt * 16 * 128 + po);
;       bf16x8 afc = *(const bf16x8*)(cA + po);
; #pragma unroll
;       for (int a = 0; a < MT; ++a) {
;         bf16x8 afn = afc;
;         if (a + 1 < MT) afn = *(const bf16x8*)(cA + (a + 1) * 16 * 128 + po);
;         __builtin_amdgcn_sched_barrier(0);
; #pragma unroll
;         for (int nt = 0; nt < 4; ++nt) acc[a][nt] = MFMA16(bf[nt], afc, acc[a][nt]);
;         __builtin_amdgcn_sched_barrier(0);
;         afc = afn;
;       }
;     }
;     asm volatile("s_waitcnt vmcnt(0)" ::: "memory");
;     __syncthreads();
;   }
	v_mfma_f32_16x16x32_bf16 v[62:65], v[150:153], v[170:173], v[62:65]
	v_mfma_f32_16x16x32_bf16 v[58:61], v[154:157], v[170:173], v[58:61]
	v_mfma_f32_16x16x32_bf16 v[54:57], v[158:161], v[170:173], v[54:57]
	v_mfma_f32_16x16x32_bf16 v[50:53], v[162:165], v[170:173], v[50:53]
	ds_read_b128 v[170:173], v149 offset:14336
	s_waitcnt lgkmcnt(2)
	v_mfma_f32_16x16x32_bf16 v[46:49], v[150:153], v[184:187], v[46:49]
	v_mfma_f32_16x16x32_bf16 v[42:45], v[154:157], v[184:187], v[42:45]
	v_mfma_f32_16x16x32_bf16 v[38:41], v[158:161], v[184:187], v[38:41]
	v_mfma_f32_16x16x32_bf16 v[34:37], v[162:165], v[184:187], v[34:37]
	s_waitcnt lgkmcnt(1)
	v_mfma_f32_16x16x32_bf16 v[30:33], v[150:153], v[166:169], v[30:33]
	v_mfma_f32_16x16x32_bf16 v[26:29], v[154:157], v[166:169], v[26:29]
	v_mfma_f32_16x16x32_bf16 v[22:25], v[158:161], v[166:169], v[22:25]
	v_mfma_f32_16x16x32_bf16 v[18:21], v[162:165], v[166:169], v[18:21]
	s_waitcnt lgkmcnt(0)
	v_mfma_f32_16x16x32_bf16 v[14:17], v[150:153], v[170:173], v[14:17]
	v_mfma_f32_16x16x32_bf16 v[10:13], v[154:157], v[170:173], v[10:13]
	v_mfma_f32_16x16x32_bf16 v[6:9], v[158:161], v[170:173], v[6:9]
	v_mfma_f32_16x16x32_bf16 v[2:5], v[162:165], v[170:173], v[2:5]
	s_cmpk_eq_i32 s16, 0x1580
	s_waitcnt vmcnt(0)
	s_barrier
	s_cbranch_scc0 .LBB0_48
	s_add_i32 s16, 0, 0x10000
	v_add_u32_e32 v138, s16, v148
	v_readlane_b32 s16, v254, 18
	s_nop 1
	v_add_u32_e32 v139, s16, v147
	v_add_u32_e32 v145, v139, v146
	ds_read_b128 v[130:133], v145
	ds_read_b128 v[134:137], v145 offset:2048
	ds_read_b128 v[148:151], v145 offset:4096
	ds_read_b128 v[152:155], v145 offset:6144
	v_add_u32_e32 v145, v138, v146
	ds_read_b128 v[156:159], v145
	ds_read_b128 v[160:163], v145 offset:2048
	s_waitcnt lgkmcnt(1)
	v_mfma_f32_16x16x32_bf16 v[126:129], v[130:133], v[156:159], v[126:129]
	v_mfma_f32_16x16x32_bf16 v[122:125], v[134:137], v[156:159], v[122:125]
	v_mfma_f32_16x16x32_bf16 v[118:121], v[148:151], v[156:159], v[118:121]
	v_mfma_f32_16x16x32_bf16 v[114:117], v[152:155], v[156:159], v[114:117]
	ds_read_b128 v[156:159], v145 offset:4096
	s_waitcnt lgkmcnt(1)
	v_mfma_f32_16x16x32_bf16 v[110:113], v[130:133], v[160:163], v[110:113]
	v_mfma_f32_16x16x32_bf16 v[106:109], v[134:137], v[160:163], v[106:109]
	v_mfma_f32_16x16x32_bf16 v[102:105], v[148:151], v[160:163], v[102:105]
	v_mfma_f32_16x16x32_bf16 v[98:101], v[152:155], v[160:163], v[98:101]
	ds_read_b128 v[160:163], v145 offset:6144
	s_waitcnt lgkmcnt(1)
	v_mfma_f32_16x16x32_bf16 v[94:97], v[130:133], v[156:159], v[94:97]
	v_mfma_f32_16x16x32_bf16 v[90:93], v[134:137], v[156:159], v[90:93]
	v_mfma_f32_16x16x32_bf16 v[86:89], v[148:151], v[156:159], v[86:89]
	v_mfma_f32_16x16x32_bf16 v[82:85], v[152:155], v[156:159], v[82:85]
	ds_read_b128 v[156:159], v145 offset:8192
	s_waitcnt lgkmcnt(1)
	v_mfma_f32_16x16x32_bf16 v[78:81], v[130:133], v[160:163], v[78:81]
	v_mfma_f32_16x16x32_bf16 v[74:77], v[134:137], v[160:163], v[74:77]
	v_mfma_f32_16x16x32_bf16 v[70:73], v[148:151], v[160:163], v[70:73]
	v_mfma_f32_16x16x32_bf16 v[66:69], v[152:155], v[160:163], v[66:69]
	ds_read_b128 v[160:163], v145 offset:10240
	s_waitcnt lgkmcnt(1)
	v_mfma_f32_16x16x32_bf16 v[62:65], v[130:133], v[156:159], v[62:65]
	v_mfma_f32_16x16x32_bf16 v[58:61], v[134:137], v[156:159], v[58:61]
	v_mfma_f32_16x16x32_bf16 v[54:57], v[148:151], v[156:159], v[54:57]
	v_mfma_f32_16x16x32_bf16 v[50:53], v[152:155], v[156:159], v[50:53]
	ds_read_b128 v[156:159], v145 offset:12288
	s_waitcnt lgkmcnt(1)
	v_mfma_f32_16x16x32_bf16 v[46:49], v[130:133], v[160:163], v[46:49]
	v_mfma_f32_16x16x32_bf16 v[42:45], v[134:137], v[160:163], v[42:45]
	v_mfma_f32_16x16x32_bf16 v[38:41], v[148:151], v[160:163], v[38:41]
	v_mfma_f32_16x16x32_bf16 v[34:37], v[152:155], v[160:163], v[34:37]
	ds_read_b128 v[160:163], v145 offset:14336
	s_waitcnt lgkmcnt(1)
	v_mfma_f32_16x16x32_bf16 v[30:33], v[130:133], v[156:159], v[30:33]
	v_mfma_f32_16x16x32_bf16 v[26:29], v[134:137], v[156:159], v[26:29]
	v_mfma_f32_16x16x32_bf16 v[22:25], v[148:151], v[156:159], v[22:25]
	v_mfma_f32_16x16x32_bf16 v[18:21], v[152:155], v[156:159], v[18:21]
	s_waitcnt lgkmcnt(0)
	v_mfma_f32_16x16x32_bf16 v[14:17], v[130:133], v[160:163], v[14:17]
	v_mfma_f32_16x16x32_bf16 v[10:13], v[134:137], v[160:163], v[10:13]
	v_mfma_f32_16x16x32_bf16 v[6:9], v[148:151], v[160:163], v[6:9]
	v_mfma_f32_16x16x32_bf16 v[2:5], v[152:155], v[160:163], v[2:5]
	v_add_u32_e32 v139, v139, v144
	ds_read_b128 v[130:133], v139
	ds_read_b128 v[134:137], v139 offset:2048
	ds_read_b128 v[146:149], v139 offset:4096
	ds_read_b128 v[150:153], v139 offset:6144
	v_add_u32_e32 v138, v138, v144
	ds_read_b128 v[154:157], v138
	ds_read_b128 v[158:161], v138 offset:2048
	s_waitcnt lgkmcnt(1)
	v_mfma_f32_16x16x32_bf16 v[126:129], v[130:133], v[154:157], v[126:129]
	v_mfma_f32_16x16x32_bf16 v[122:125], v[134:137], v[154:157], v[122:125]
	v_mfma_f32_16x16x32_bf16 v[118:121], v[146:149], v[154:157], v[118:121]
	v_mfma_f32_16x16x32_bf16 v[114:117], v[150:153], v[154:157], v[114:117]
	ds_read_b128 v[154:157], v138 offset:4096
	s_waitcnt lgkmcnt(1)
	v_mfma_f32_16x16x32_bf16 v[110:113], v[130:133], v[158:161], v[110:113]
	v_mfma_f32_16x16x32_bf16 v[106:109], v[134:137], v[158:161], v[106:109]
	v_mfma_f32_16x16x32_bf16 v[102:105], v[146:149], v[158:161], v[102:105]
	v_mfma_f32_16x16x32_bf16 v[98:101], v[150:153], v[158:161], v[98:101]
	ds_read_b128 v[158:161], v138 offset:6144
	s_waitcnt lgkmcnt(1)
	v_mfma_f32_16x16x32_bf16 v[94:97], v[130:133], v[154:157], v[94:97]
	v_mfma_f32_16x16x32_bf16 v[90:93], v[134:137], v[154:157], v[90:93]
	v_mfma_f32_16x16x32_bf16 v[86:89], v[146:149], v[154:157], v[86:89]
	v_mfma_f32_16x16x32_bf16 v[82:85], v[150:153], v[154:157], v[82:85]
	ds_read_b128 v[154:157], v138 offset:8192
	s_waitcnt lgkmcnt(1)
; DI const float* xsrc_row(const Params& p, bool first, int row) {
;   int b = row / TT, t = row - b * TT;
;   if (t < CTXL) return (first ? p.ctx : p.Xc) + ((size_t)b * CTXL + t) * DM;
;   return (first ? p.x : p.out) + ((size_t)b * SEQ + (t - CTXL)) * DM;
; }
; DI float* xdst_row(const Params& p, int row) {
;   int b = row / TT, t = row - b * TT;
;   if (t < CTXL) return p.Xc + ((size_t)b * CTXL + t) * DM;
;   return p.out + ((size_t)b * SEQ + (t - CTXL)) * DM;
; }
; DI void phase_resid(char* smem, const Params& p, int layer, const bf16_t* A, int K, const bf16_t* W, int gate_idx, bool first) {
;     ...
;   auto ep = [&](int row, int col, float v0, float v1, float v2, float v3) {
;     const int b = row / TT, t = row - b * TT;
;     const float4 g = *(const float4*)(p.mod + (size_t)(layer * 5 + (t < CTXL ? 4 : b)) * 6144 + gate_idx * 1024 + col);
;     const float4 xo = *(const float4*)(xsrc_row(p, first, row) + col);
;     *(float4*)(xdst_row(p, row) + col) = make_float4(xo.x + g.x * v0, xo.y + g.y * v1, xo.z + g.z * v2, xo.w + g.w * v3);
;   };
	v_mfma_f32_16x16x32_bf16 v[78:81], v[130:133], v[158:161], v[78:81]
	v_mfma_f32_16x16x32_bf16 v[74:77], v[134:137], v[158:161], v[74:77]
	v_mfma_f32_16x16x32_bf16 v[70:73], v[146:149], v[158:161], v[70:73]
	v_mfma_f32_16x16x32_bf16 v[66:69], v[150:153], v[158:161], v[66:69]
	ds_read_b128 v[158:161], v138 offset:10240
	s_waitcnt lgkmcnt(1)
	v_mfma_f32_16x16x32_bf16 v[62:65], v[130:133], v[154:157], v[62:65]
	v_mfma_f32_16x16x32_bf16 v[58:61], v[134:137], v[154:157], v[58:61]
	v_mfma_f32_16x16x32_bf16 v[54:57], v[146:149], v[154:157], v[54:57]
	v_mfma_f32_16x16x32_bf16 v[50:53], v[150:153], v[154:157], v[50:53]
	ds_read_b128 v[154:157], v138 offset:12288
	s_waitcnt lgkmcnt(1)
	v_mfma_f32_16x16x32_bf16 v[46:49], v[130:133], v[158:161], v[46:49]
	v_mfma_f32_16x16x32_bf16 v[42:45], v[134:137], v[158:161], v[42:45]
	v_mfma_f32_16x16x32_bf16 v[38:41], v[146:149], v[158:161], v[38:41]
	v_mfma_f32_16x16x32_bf16 v[34:37], v[150:153], v[158:161], v[34:37]
	ds_read_b128 v[158:161], v138 offset:14336
	s_waitcnt lgkmcnt(1)
	v_mfma_f32_16x16x32_bf16 v[30:33], v[130:133], v[154:157], v[30:33]
	v_mfma_f32_16x16x32_bf16 v[26:29], v[134:137], v[154:157], v[26:29]
	v_mfma_f32_16x16x32_bf16 v[22:25], v[146:149], v[154:157], v[22:25]
	v_mfma_f32_16x16x32_bf16 v[18:21], v[150:153], v[154:157], v[18:21]
	s_waitcnt lgkmcnt(0)
	v_mfma_f32_16x16x32_bf16 v[14:17], v[130:133], v[158:161], v[14:17]
	v_mfma_f32_16x16x32_bf16 v[10:13], v[134:137], v[158:161], v[10:13]
	v_mfma_f32_16x16x32_bf16 v[6:9], v[146:149], v[158:161], v[6:9]
	v_mfma_f32_16x16x32_bf16 v[2:5], v[150:153], v[158:161], v[2:5]
	v_or_b32_e32 v131, s40, v142
	v_lshlrev_b32_e32 v130, 6, v143
	v_lshl_add_u32 v142, v140, 7, v131
	v_lshlrev_b32_e32 v131, 2, v141
	v_or3_b32 v134, v130, v131, s39
	v_mul_hi_i32 v130, v142, s1
	v_lshrrev_b32_e32 v131, 31, v130
	v_ashrrev_i32_e32 v130, 11, v130
	v_add_u32_e32 v130, v130, v131
	v_mad_i32_i24 v131, v130, s90, v142
	s_movk_i32 s39, 0x100
	v_cmp_gt_i32_e32 vcc, s39, v131
	v_add_u32_e32 v132, 0xffffff00, v131
	v_ashrrev_i32_e32 v133, 31, v131
	v_readlane_b32 s40, v254, 1
	v_cndmask_b32_e64 v135, v130, 4, vcc
	v_cndmask_b32_e32 v133, 0, v133, vcc
	v_cndmask_b32_e32 v132, v132, v131, vcc
	v_ashrrev_i32_e32 v131, 31, v130
	v_cndmask_b32_e64 v136, 25, 20, vcc
	v_readlane_b32 s41, v254, 2
	v_lshlrev_b64 v[140:141], v136, v[130:131]
	v_lshlrev_b64 v[150:151], 12, v[132:133]
	v_add_u32_e32 v130, s37, v135
	v_mov_b64_e32 v[132:133], s[40:41]
	s_movk_i32 s40, 0x6000
	v_readlane_b32 s42, v254, 3
	v_readlane_b32 s43, v254, 4
	v_mad_i64_i32 v[130:131], s[16:17], v130, s40, v[132:133]
	s_mov_b64 s[42:43], 0x5000
	v_ashrrev_i32_e32 v135, 31, v134
	v_readlane_b32 s16, v252, 26
	v_lshl_add_u64 v[136:137], v[130:131], 0, s[42:43]
	v_lshlrev_b64 v[130:131], 2, v[134:135]
	v_mov_b32_e32 v135, s16
	v_readlane_b32 s16, v252, 28
	s_waitcnt vmcnt(0)
	s_barrier
	s_nop 0
	v_mov_b32_e32 v143, s16
	v_readlane_b32 s16, v252, 25
	v_cndmask_b32_e32 v139, v135, v143, vcc
	s_nop 0
	v_mov_b32_e32 v144, s16
	v_readlane_b32 s16, v252, 27
	v_readlane_b32 s68, v252, 5
	v_readlane_b32 s80, v252, 17
	v_mov_b32_e32 v145, s16
	v_cndmask_b32_e32 v138, v144, v145, vcc
	global_load_dwordx2 v[138:139], v[138:139], off
	v_readlane_b32 s81, v252, 18
	v_readlane_b32 s82, v252, 19
	v_readlane_b32 s83, v252, 20
	v_mov_b32_e32 v146, s81
	v_mov_b32_e32 v148, s80
	v_mov_b32_e32 v147, s83
	v_mov_b32_e32 v149, s82
	v_cndmask_b32_e32 v155, v146, v147, vcc
	v_cndmask_b32_e32 v154, v148, v149, vcc
	v_lshl_add_u64 v[152:153], v[136:137], 0, v[130:131]
	s_add_i32 s38, s38, s30
	s_cmp_gt_i32 s38, 31
	v_readlane_b32 s44, v254, 5
	v_readlane_b32 s45, v254, 6
	v_readlane_b32 s46, v254, 7
	v_readlane_b32 s47, v254, 8
	v_readlane_b32 s48, v254, 9
	v_readlane_b32 s49, v254, 10
	v_readlane_b32 s50, v254, 11
	v_readlane_b32 s51, v254, 12
	v_readlane_b32 s52, v254, 13
	v_readlane_b32 s53, v254, 14
	v_readlane_b32 s54, v254, 15
	v_readlane_b32 s55, v254, 16
	v_readlane_b32 s69, v252, 6
	v_readlane_b32 s70, v252, 7
	v_readlane_b32 s71, v252, 8
	v_readlane_b32 s72, v252, 9
	v_readlane_b32 s73, v252, 10
	v_readlane_b32 s74, v252, 11
	v_readlane_b32 s75, v252, 12
	v_readlane_b32 s76, v252, 13
	v_readlane_b32 s77, v252, 14
	v_readlane_b32 s78, v252, 15
	v_readlane_b32 s79, v252, 16
	s_waitcnt vmcnt(0)
	v_lshl_add_u64 v[138:139], v[138:139], 0, v[140:141]
	v_lshl_add_u64 v[138:139], v[138:139], 0, v[150:151]
	v_lshl_add_u64 v[140:141], v[154:155], 0, v[140:141]
	v_lshl_add_u64 v[138:139], v[138:139], 0, v[130:131]
	v_lshl_add_u64 v[140:141], v[140:141], 0, v[150:151]
	v_lshl_add_u64 v[140:141], v[140:141], 0, v[130:131]
	s_cselect_b64 s[16:17], -1, 0
	global_load_dwordx4 v[156:159], v[152:153], off
	global_load_dwordx4 v[160:163], v[152:153], off offset:64
	global_load_dwordx4 v[164:167], v[152:153], off offset:128
	global_load_dwordx4 v[168:171], v[152:153], off offset:192
	global_load_dwordx4 v[172:175], v[138:139], off
	global_load_dwordx4 v[176:179], v[138:139], off offset:64
	global_load_dwordx4 v[180:183], v[138:139], off offset:128
	global_load_dwordx4 v[184:187], v[138:139], off offset:192
	v_add_co_u32_e32 v138, vcc, 0x10000, v138
	s_nop 1
	v_addc_co_u32_e32 v139, vcc, 0, v139, vcc
	global_load_dwordx4 v[198:201], v[138:139], off
	global_load_dwordx4 v[202:205], v[138:139], off offset:64
	global_load_dwordx4 v[206:209], v[138:139], off offset:128
	global_load_dwordx4 v[210:213], v[138:139], off offset:192
	v_add_co_u32_e32 v138, vcc, 0x10000, v138
	s_nop 1
	v_addc_co_u32_e32 v139, vcc, 0, v139, vcc
	global_load_dwordx4 v[214:217], v[138:139], off
	global_load_dwordx4 v[218:221], v[138:139], off offset:64
	global_load_dwordx4 v[222:225], v[138:139], off offset:128
	global_load_dwordx4 v[142:145], v[138:139], off offset:192
	v_add_co_u32_e32 v138, vcc, 0x10000, v138
	s_nop 1
	v_addc_co_u32_e32 v139, vcc, 0, v139, vcc
	s_waitcnt vmcnt(8)
; DI void phase_resid(char* smem, const Params& p, int layer, const bf16_t* A, int K, const bf16_t* W, int gate_idx, bool first) {
;     ...
;   auto ep = [&](int row, int col, float v0, float v1, float v2, float v3) {
;     const int b = row / TT, t = row - b * TT;
;     const float4 g = *(const float4*)(p.mod + (size_t)(layer * 5 + (t < CTXL ? 4 : b)) * 6144 + gate_idx * 1024 + col);
;     const float4 xo = *(const float4*)(xsrc_row(p, first, row) + col);
;     *(float4*)(xdst_row(p, row) + col) = make_float4(xo.x + g.x * v0, xo.y + g.y * v1, xo.z + g.z * v2, xo.w + g.w * v3);
;   };
	v_pk_fma_f32 v[126:127], v[126:127], v[156:157], v[172:173]
	v_pk_fma_f32 v[128:129], v[128:129], v[158:159], v[174:175]
	v_pk_fma_f32 v[122:123], v[122:123], v[160:161], v[176:177]
	v_pk_fma_f32 v[124:125], v[124:125], v[162:163], v[178:179]
	v_pk_fma_f32 v[118:119], v[118:119], v[164:165], v[180:181]
	v_pk_fma_f32 v[120:121], v[120:121], v[166:167], v[182:183]
	v_pk_fma_f32 v[114:115], v[114:115], v[168:169], v[184:185]
	v_pk_fma_f32 v[116:117], v[116:117], v[170:171], v[186:187]
	global_store_dwordx4 v[140:141], v[126:129], off
	global_store_dwordx4 v[140:141], v[122:125], off offset:64
	global_store_dwordx4 v[140:141], v[118:121], off offset:128
	global_store_dwordx4 v[140:141], v[114:117], off offset:192
	v_add_co_u32_e32 v140, vcc, 0x10000, v140
	s_nop 1
	v_addc_co_u32_e32 v141, vcc, 0, v141, vcc
	global_load_dwordx4 v[172:175], v[138:139], off
	global_load_dwordx4 v[176:179], v[138:139], off offset:64
	global_load_dwordx4 v[180:183], v[138:139], off offset:128
	global_load_dwordx4 v[184:187], v[138:139], off offset:192
	v_add_co_u32_e32 v138, vcc, 0x10000, v138
	s_nop 1
	v_addc_co_u32_e32 v139, vcc, 0, v139, vcc
	s_waitcnt vmcnt(12)
	v_pk_fma_f32 v[110:111], v[110:111], v[156:157], v[198:199]
	v_pk_fma_f32 v[112:113], v[112:113], v[158:159], v[200:201]
	v_pk_fma_f32 v[106:107], v[106:107], v[160:161], v[202:203]
	v_pk_fma_f32 v[108:109], v[108:109], v[162:163], v[204:205]
	v_pk_fma_f32 v[102:103], v[102:103], v[164:165], v[206:207]
	v_pk_fma_f32 v[104:105], v[104:105], v[166:167], v[208:209]
	v_pk_fma_f32 v[98:99], v[98:99], v[168:169], v[210:211]
	v_pk_fma_f32 v[100:101], v[100:101], v[170:171], v[212:213]
	global_store_dwordx4 v[140:141], v[110:113], off
	global_store_dwordx4 v[140:141], v[106:109], off offset:64
	global_store_dwordx4 v[140:141], v[102:105], off offset:128
	global_store_dwordx4 v[140:141], v[98:101], off offset:192
	v_add_co_u32_e32 v140, vcc, 0x10000, v140
	s_nop 1
	v_addc_co_u32_e32 v141, vcc, 0, v141, vcc
	global_load_dwordx4 v[198:201], v[138:139], off
	global_load_dwordx4 v[202:205], v[138:139], off offset:64
	global_load_dwordx4 v[206:209], v[138:139], off offset:128
	global_load_dwordx4 v[210:213], v[138:139], off offset:192
	v_add_co_u32_e32 v138, vcc, 0x10000, v138
	s_nop 1
	v_addc_co_u32_e32 v139, vcc, 0, v139, vcc
	s_waitcnt vmcnt(16)
	v_pk_fma_f32 v[94:95], v[94:95], v[156:157], v[214:215]
	v_pk_fma_f32 v[96:97], v[96:97], v[158:159], v[216:217]
	v_pk_fma_f32 v[90:91], v[90:91], v[160:161], v[218:219]
	v_pk_fma_f32 v[92:93], v[92:93], v[162:163], v[220:221]
	v_pk_fma_f32 v[86:87], v[86:87], v[164:165], v[222:223]
	v_pk_fma_f32 v[88:89], v[88:89], v[166:167], v[224:225]
	v_pk_fma_f32 v[82:83], v[82:83], v[168:169], v[142:143]
	v_pk_fma_f32 v[84:85], v[84:85], v[170:171], v[144:145]
	global_store_dwordx4 v[140:141], v[94:97], off
	global_store_dwordx4 v[140:141], v[90:93], off offset:64
	global_store_dwordx4 v[140:141], v[86:89], off offset:128
	global_store_dwordx4 v[140:141], v[82:85], off offset:192
	v_add_co_u32_e32 v140, vcc, 0x10000, v140
	s_nop 1
	v_addc_co_u32_e32 v141, vcc, 0, v141, vcc
	global_load_dwordx4 v[214:217], v[138:139], off
	global_load_dwordx4 v[218:221], v[138:139], off offset:64
	global_load_dwordx4 v[222:225], v[138:139], off offset:128
	global_load_dwordx4 v[142:145], v[138:139], off offset:192
	v_add_co_u32_e32 v138, vcc, 0x10000, v138
	s_nop 1
	v_addc_co_u32_e32 v139, vcc, 0, v139, vcc
	s_waitcnt vmcnt(16)
; DI void phase_resid(char* smem, const Params& p, int layer, const bf16_t* A, int K, const bf16_t* W, int gate_idx, bool first) {
;     ...
;   auto ep = [&](int row, int col, float v0, float v1, float v2, float v3) {
;     const int b = row / TT, t = row - b * TT;
;     const float4 g = *(const float4*)(p.mod + (size_t)(layer * 5 + (t < CTXL ? 4 : b)) * 6144 + gate_idx * 1024 + col);
;     const float4 xo = *(const float4*)(xsrc_row(p, first, row) + col);
;     *(float4*)(xdst_row(p, row) + col) = make_float4(xo.x + g.x * v0, xo.y + g.y * v1, xo.z + g.z * v2, xo.w + g.w * v3);
;   };
	v_pk_fma_f32 v[78:79], v[78:79], v[156:157], v[172:173]
	v_pk_fma_f32 v[80:81], v[80:81], v[158:159], v[174:175]
	v_pk_fma_f32 v[74:75], v[74:75], v[160:161], v[176:177]
	v_pk_fma_f32 v[76:77], v[76:77], v[162:163], v[178:179]
	v_pk_fma_f32 v[70:71], v[70:71], v[164:165], v[180:181]
	v_pk_fma_f32 v[72:73], v[72:73], v[166:167], v[182:183]
	v_pk_fma_f32 v[66:67], v[66:67], v[168:169], v[184:185]
	v_pk_fma_f32 v[68:69], v[68:69], v[170:171], v[186:187]
	global_store_dwordx4 v[140:141], v[78:81], off
	global_store_dwordx4 v[140:141], v[74:77], off offset:64
	global_store_dwordx4 v[140:141], v[70:73], off offset:128
	global_store_dwordx4 v[140:141], v[66:69], off offset:192
	v_add_co_u32_e32 v140, vcc, 0x10000, v140
	s_nop 1
	v_addc_co_u32_e32 v141, vcc, 0, v141, vcc
	global_load_dwordx4 v[172:175], v[138:139], off
	global_load_dwordx4 v[176:179], v[138:139], off offset:64
	global_load_dwordx4 v[180:183], v[138:139], off offset:128
	global_load_dwordx4 v[184:187], v[138:139], off offset:192
	v_add_co_u32_e32 v138, vcc, 0x10000, v138
	s_nop 1
	v_addc_co_u32_e32 v139, vcc, 0, v139, vcc
	s_waitcnt vmcnt(16)
	v_pk_fma_f32 v[62:63], v[62:63], v[156:157], v[198:199]
	v_pk_fma_f32 v[64:65], v[64:65], v[158:159], v[200:201]
	v_pk_fma_f32 v[58:59], v[58:59], v[160:161], v[202:203]
	v_pk_fma_f32 v[60:61], v[60:61], v[162:163], v[204:205]
	v_pk_fma_f32 v[54:55], v[54:55], v[164:165], v[206:207]
	v_pk_fma_f32 v[56:57], v[56:57], v[166:167], v[208:209]
	v_pk_fma_f32 v[50:51], v[50:51], v[168:169], v[210:211]
	v_pk_fma_f32 v[52:53], v[52:53], v[170:171], v[212:213]
	global_store_dwordx4 v[140:141], v[62:65], off
	global_store_dwordx4 v[140:141], v[58:61], off offset:64
	global_store_dwordx4 v[140:141], v[54:57], off offset:128
	global_store_dwordx4 v[140:141], v[50:53], off offset:192
	v_add_co_u32_e32 v140, vcc, 0x10000, v140
	s_nop 1
	v_addc_co_u32_e32 v141, vcc, 0, v141, vcc
	global_load_dwordx4 v[198:201], v[138:139], off
	global_load_dwordx4 v[202:205], v[138:139], off offset:64
	global_load_dwordx4 v[206:209], v[138:139], off offset:128
	global_load_dwordx4 v[210:213], v[138:139], off offset:192
	s_waitcnt vmcnt(16)
	v_pk_fma_f32 v[46:47], v[46:47], v[156:157], v[214:215]
	v_pk_fma_f32 v[48:49], v[48:49], v[158:159], v[216:217]
	v_pk_fma_f32 v[42:43], v[42:43], v[160:161], v[218:219]
	v_pk_fma_f32 v[44:45], v[44:45], v[162:163], v[220:221]
	v_pk_fma_f32 v[38:39], v[38:39], v[164:165], v[222:223]
	v_pk_fma_f32 v[40:41], v[40:41], v[166:167], v[224:225]
	v_pk_fma_f32 v[34:35], v[34:35], v[168:169], v[142:143]
	v_pk_fma_f32 v[36:37], v[36:37], v[170:171], v[144:145]
	global_store_dwordx4 v[140:141], v[46:49], off
	global_store_dwordx4 v[140:141], v[42:45], off offset:64
	global_store_dwordx4 v[140:141], v[38:41], off offset:128
	global_store_dwordx4 v[140:141], v[34:37], off offset:192
	v_add_co_u32_e32 v140, vcc, 0x10000, v140
	s_nop 1
	v_addc_co_u32_e32 v141, vcc, 0, v141, vcc
	s_waitcnt vmcnt(12)
	v_pk_fma_f32 v[30:31], v[30:31], v[156:157], v[172:173]
	v_pk_fma_f32 v[32:33], v[32:33], v[158:159], v[174:175]
	v_pk_fma_f32 v[26:27], v[26:27], v[160:161], v[176:177]
	v_pk_fma_f32 v[28:29], v[28:29], v[162:163], v[178:179]
	v_pk_fma_f32 v[22:23], v[22:23], v[164:165], v[180:181]
	v_pk_fma_f32 v[24:25], v[24:25], v[166:167], v[182:183]
	v_pk_fma_f32 v[18:19], v[18:19], v[168:169], v[184:185]
	v_pk_fma_f32 v[20:21], v[20:21], v[170:171], v[186:187]
	global_store_dwordx4 v[140:141], v[30:33], off
	global_store_dwordx4 v[140:141], v[26:29], off offset:64
	global_store_dwordx4 v[140:141], v[22:25], off offset:128
	global_store_dwordx4 v[140:141], v[18:21], off offset:192
	v_add_co_u32_e32 v140, vcc, 0x10000, v140
	s_nop 1
	v_addc_co_u32_e32 v141, vcc, 0, v141, vcc
	s_waitcnt vmcnt(8)
	v_pk_fma_f32 v[14:15], v[14:15], v[156:157], v[198:199]
	v_pk_fma_f32 v[16:17], v[16:17], v[158:159], v[200:201]
	v_pk_fma_f32 v[10:11], v[10:11], v[160:161], v[202:203]
	v_pk_fma_f32 v[12:13], v[12:13], v[162:163], v[204:205]
	v_pk_fma_f32 v[6:7], v[6:7], v[164:165], v[206:207]
	v_pk_fma_f32 v[8:9], v[8:9], v[166:167], v[208:209]
	v_pk_fma_f32 v[2:3], v[2:3], v[168:169], v[210:211]
	v_pk_fma_f32 v[4:5], v[4:5], v[170:171], v[212:213]
	global_store_dwordx4 v[140:141], v[14:17], off
	global_store_dwordx4 v[140:141], v[10:13], off offset:64
	global_store_dwordx4 v[140:141], v[6:9], off offset:128
	global_store_dwordx4 v[140:141], v[2:5], off offset:192
	s_branch .LBB0_41

; #define MFMA16(a, b, c) __builtin_amdgcn_mfma_f32_16x16x32_bf16((a), (b), (c), 0, 0, 0)
;     ...
;   for (int kt = 0; kt < nk; ++kt) {
;     const int buf = kt & 1;
;     const char* cA = smem + buf * STAGE + (wm * 32 * MI + r16) * 128;
;     const char* cB = smem + buf * STAGE + 32768 + (wn * 64 + r16) * 128;
; #pragma unroll
;     for (int k2 = 0; k2 < 2; ++k2) {
;       if (k2 == 1 && kt + 1 < nk) STAGE_TILE(buf ^ 1, (kt + 1) * 64)
;       const int po = ((4 * k2 + q4) ^ swz) * 16;
;       bf16x8 bf[4];
; #pragma unroll
;       for (int nt = 0; nt < 4; ++nt) bf[nt] = *(const bf16x8*)(cB + nt * 16 * 128 + po);
;       bf16x8 afc = *(const bf16x8*)(cA + po);
; #pragma unroll
;       for (int a = 0; a < MT; ++a) {
;         bf16x8 afn = afc;
;         if (a + 1 < MT) afn = *(const bf16x8*)(cA + (a + 1) * 16 * 128 + po);
;         __builtin_amdgcn_sched_barrier(0);
; #pragma unroll
;         for (int nt = 0; nt < 4; ++nt) acc[a][nt] = MFMA16(bf[nt], afc, acc[a][nt]);
;         __builtin_amdgcn_sched_barrier(0);
;         afc = afn;
;       }
;     }
;     asm volatile("s_waitcnt vmcnt(0)" ::: "memory");
;     __syncthreads();
;   }
.LBB0_75:
	s_and_b32 s41, s40, 0x10000
	s_add_i32 s42, s41, 0
	v_add_u32_e32 v190, s42, v147
	v_add_u32_e32 v162, v190, v146
	v_add_u32_e32 v149, s42, v148
	v_add_u32_e32 v202, v149, v146
	s_xor_b32 s41, s41, 0x10000
	ds_read_b128 v[150:153], v162 offset:32768
	ds_read_b128 v[166:169], v202
	ds_read_b128 v[154:157], v162 offset:34816
	ds_read_b128 v[158:161], v162 offset:36864
	ds_read_b128 v[162:165], v162 offset:38912
	ds_read_b128 v[170:173], v202 offset:2048
	ds_read_b128 v[184:187], v202 offset:4096
	s_waitcnt lgkmcnt(5)
	v_mfma_f32_16x16x32_bf16 v[126:129], v[150:153], v[166:169], v[126:129]
	v_readfirstlane_b32 s42, v145
	s_waitcnt lgkmcnt(4)
	v_mfma_f32_16x16x32_bf16 v[122:125], v[154:157], v[166:169], v[122:125]
	s_nop 0
	s_waitcnt lgkmcnt(3)
	v_mfma_f32_16x16x32_bf16 v[118:121], v[158:161], v[166:169], v[118:121]
	s_add_u32 s42, s42, s41
	s_waitcnt lgkmcnt(2)
	v_mfma_f32_16x16x32_bf16 v[114:117], v[162:165], v[166:169], v[114:117]
	ds_read_b128 v[166:169], v202 offset:6144
	s_waitcnt lgkmcnt(2)
	v_mfma_f32_16x16x32_bf16 v[110:113], v[150:153], v[170:173], v[110:113]
	s_add_u32 m0, s42, 0x0
	v_mfma_f32_16x16x32_bf16 v[106:109], v[154:157], v[170:173], v[106:109]
	global_load_lds_dwordx4 v174, s[100:101]
	v_mfma_f32_16x16x32_bf16 v[102:105], v[158:161], v[170:173], v[102:105]
	s_add_u32 m0, s42, 0x2000
	v_mfma_f32_16x16x32_bf16 v[98:101], v[162:165], v[170:173], v[98:101]
	ds_read_b128 v[170:173], v202 offset:8192
	s_waitcnt lgkmcnt(2)
	v_mfma_f32_16x16x32_bf16 v[94:97], v[150:153], v[184:187], v[94:97]
	global_load_lds_dwordx4 v175, s[100:101]
	v_mfma_f32_16x16x32_bf16 v[90:93], v[154:157], v[184:187], v[90:93]
	s_add_u32 m0, s42, 0x4000
	v_mfma_f32_16x16x32_bf16 v[86:89], v[158:161], v[184:187], v[86:89]
	global_load_lds_dwordx4 v176, s[100:101]
	v_mfma_f32_16x16x32_bf16 v[82:85], v[162:165], v[184:187], v[82:85]
	ds_read_b128 v[184:187], v202 offset:10240
	s_waitcnt lgkmcnt(2)
	v_mfma_f32_16x16x32_bf16 v[78:81], v[150:153], v[166:169], v[78:81]
	s_add_u32 m0, s42, 0x6000
	v_mfma_f32_16x16x32_bf16 v[74:77], v[154:157], v[166:169], v[74:77]
	global_load_lds_dwordx4 v177, s[100:101]
	v_mfma_f32_16x16x32_bf16 v[70:73], v[158:161], v[166:169], v[70:73]
	s_add_u32 m0, s42, 0x8000
	v_mfma_f32_16x16x32_bf16 v[66:69], v[162:165], v[166:169], v[66:69]
	ds_read_b128 v[166:169], v202 offset:12288
	s_waitcnt lgkmcnt(2)
	v_mfma_f32_16x16x32_bf16 v[62:65], v[150:153], v[170:173], v[62:65]
	global_load_lds_dwordx4 v178, s[100:101]
	v_mfma_f32_16x16x32_bf16 v[58:61], v[154:157], v[170:173], v[58:61]
	s_add_u32 m0, s42, 0xa000
	v_mfma_f32_16x16x32_bf16 v[54:57], v[158:161], v[170:173], v[54:57]
	global_load_lds_dwordx4 v179, s[100:101]
	v_mfma_f32_16x16x32_bf16 v[50:53], v[162:165], v[170:173], v[50:53]
	ds_read_b128 v[170:173], v202 offset:14336
	s_waitcnt lgkmcnt(2)
	v_mfma_f32_16x16x32_bf16 v[46:49], v[150:153], v[184:187], v[46:49]
	s_add_u32 m0, s42, 0xc000
	v_mfma_f32_16x16x32_bf16 v[42:45], v[154:157], v[184:187], v[42:45]
	global_load_lds_dwordx4 v180, s[100:101]
	v_mfma_f32_16x16x32_bf16 v[38:41], v[158:161], v[184:187], v[38:41]
	s_add_u32 m0, s42, 0xe000
	v_mfma_f32_16x16x32_bf16 v[34:37], v[162:165], v[184:187], v[34:37]
	s_waitcnt lgkmcnt(1)
	v_mfma_f32_16x16x32_bf16 v[30:33], v[150:153], v[166:169], v[30:33]
	global_load_lds_dwordx4 v181, s[100:101]
	v_mfma_f32_16x16x32_bf16 v[26:29], v[154:157], v[166:169], v[26:29]
	v_mfma_f32_16x16x32_bf16 v[22:25], v[158:161], v[166:169], v[22:25]
	v_mfma_f32_16x16x32_bf16 v[18:21], v[162:165], v[166:169], v[18:21]
	s_waitcnt lgkmcnt(0)
	v_mfma_f32_16x16x32_bf16 v[14:17], v[150:153], v[170:173], v[14:17]
	v_mfma_f32_16x16x32_bf16 v[10:13], v[154:157], v[170:173], v[10:13]
	v_mfma_f32_16x16x32_bf16 v[6:9], v[158:161], v[170:173], v[6:9]
	v_mfma_f32_16x16x32_bf16 v[2:5], v[162:165], v[170:173], v[2:5]
	v_add_u32_e32 v162, v190, v144
	v_add_u32_e32 v149, v149, v144
	ds_read_b128 v[150:153], v162 offset:32768
	ds_read_b128 v[166:169], v149
	ds_read_b128 v[154:157], v162 offset:34816
	ds_read_b128 v[158:161], v162 offset:36864
	ds_read_b128 v[162:165], v162 offset:38912
	ds_read_b128 v[170:173], v149 offset:2048
	ds_read_b128 v[184:187], v149 offset:4096
	s_waitcnt lgkmcnt(5)
	v_mfma_f32_16x16x32_bf16 v[126:129], v[150:153], v[166:169], v[126:129]
	s_add_u32 s100, s100, 0x80
	s_waitcnt lgkmcnt(4)
	v_mfma_f32_16x16x32_bf16 v[122:125], v[154:157], v[166:169], v[122:125]
	s_addc_u32 s101, s101, 0
	s_waitcnt lgkmcnt(3)
	v_mfma_f32_16x16x32_bf16 v[118:121], v[158:161], v[166:169], v[118:121]
	s_add_u32 s16, s16, 0x80
	s_waitcnt lgkmcnt(2)
	v_mfma_f32_16x16x32_bf16 v[114:117], v[162:165], v[166:169], v[114:117]
	ds_read_b128 v[166:169], v149 offset:6144
	s_waitcnt lgkmcnt(2)
	v_mfma_f32_16x16x32_bf16 v[110:113], v[150:153], v[170:173], v[110:113]
	s_addc_u32 s17, s17, 0
	v_mfma_f32_16x16x32_bf16 v[106:109], v[154:157], v[170:173], v[106:109]
	s_add_i32 s40, s40, 0x10000
	v_mfma_f32_16x16x32_bf16 v[102:105], v[158:161], v[170:173], v[102:105]
	v_mfma_f32_16x16x32_bf16 v[98:101], v[162:165], v[170:173], v[98:101]
	ds_read_b128 v[170:173], v149 offset:8192
	s_waitcnt lgkmcnt(2)
	v_mfma_f32_16x16x32_bf16 v[94:97], v[150:153], v[184:187], v[94:97]
	v_mfma_f32_16x16x32_bf16 v[90:93], v[154:157], v[184:187], v[90:93]
	v_mfma_f32_16x16x32_bf16 v[86:89], v[158:161], v[184:187], v[86:89]
	v_mfma_f32_16x16x32_bf16 v[82:85], v[162:165], v[184:187], v[82:85]
	ds_read_b128 v[184:187], v149 offset:10240
	s_waitcnt lgkmcnt(2)
	v_mfma_f32_16x16x32_bf16 v[78:81], v[150:153], v[166:169], v[78:81]
	v_mfma_f32_16x16x32_bf16 v[74:77], v[154:157], v[166:169], v[74:77]
	v_mfma_f32_16x16x32_bf16 v[70:73], v[158:161], v[166:169], v[70:73]
	v_mfma_f32_16x16x32_bf16 v[66:69], v[162:165], v[166:169], v[66:69]
	ds_read_b128 v[166:169], v149 offset:12288
	s_waitcnt lgkmcnt(2)
; #define MFMA16(a, b, c) __builtin_amdgcn_mfma_f32_16x16x32_bf16((a), (b), (c), 0, 0, 0)
;     ...
;   for (int kt = 0; kt < nk; ++kt) {
;     const int buf = kt & 1;
;     const char* cA = smem + buf * STAGE + (wm * 32 * MI + r16) * 128;
;     const char* cB = smem + buf * STAGE + 32768 + (wn * 64 + r16) * 128;
; #pragma unroll
;     for (int k2 = 0; k2 < 2; ++k2) {
;       if (k2 == 1 && kt + 1 < nk) STAGE_TILE(buf ^ 1, (kt + 1) * 64)
;       const int po = ((4 * k2 + q4) ^ swz) * 16;
;       bf16x8 bf[4];
; #pragma unroll
;       for (int nt = 0; nt < 4; ++nt) bf[nt] = *(const bf16x8*)(cB + nt * 16 * 128 + po);
;       bf16x8 afc = *(const bf16x8*)(cA + po);
; #pragma unroll
;       for (int a = 0; a < MT; ++a) {
;         bf16x8 afn = afc;
;         if (a + 1 < MT) afn = *(const bf16x8*)(cA + (a + 1) * 16 * 128 + po);
;         __builtin_amdgcn_sched_barrier(0);
; #pragma unroll
;         for (int nt = 0; nt < 4; ++nt) acc[a][nt] = MFMA16(bf[nt], afc, acc[a][nt]);
;         __builtin_amdgcn_sched_barrier(0);
;         afc = afn;
;       }
;     }
;     asm volatile("s_waitcnt vmcnt(0)" ::: "memory");
;     __syncthreads();
;   }
	v_mfma_f32_16x16x32_bf16 v[62:65], v[150:153], v[170:173], v[62:65]
	v_mfma_f32_16x16x32_bf16 v[58:61], v[154:157], v[170:173], v[58:61]
	v_mfma_f32_16x16x32_bf16 v[54:57], v[158:161], v[170:173], v[54:57]
	v_mfma_f32_16x16x32_bf16 v[50:53], v[162:165], v[170:173], v[50:53]
	ds_read_b128 v[170:173], v149 offset:14336
	s_waitcnt lgkmcnt(2)
	v_mfma_f32_16x16x32_bf16 v[46:49], v[150:153], v[184:187], v[46:49]
	v_mfma_f32_16x16x32_bf16 v[42:45], v[154:157], v[184:187], v[42:45]
	v_mfma_f32_16x16x32_bf16 v[38:41], v[158:161], v[184:187], v[38:41]
	v_mfma_f32_16x16x32_bf16 v[34:37], v[162:165], v[184:187], v[34:37]
	s_waitcnt lgkmcnt(1)
	v_mfma_f32_16x16x32_bf16 v[30:33], v[150:153], v[166:169], v[30:33]
	v_mfma_f32_16x16x32_bf16 v[26:29], v[154:157], v[166:169], v[26:29]
	v_mfma_f32_16x16x32_bf16 v[22:25], v[158:161], v[166:169], v[22:25]
	v_mfma_f32_16x16x32_bf16 v[18:21], v[162:165], v[166:169], v[18:21]
	s_waitcnt lgkmcnt(0)
	v_mfma_f32_16x16x32_bf16 v[14:17], v[150:153], v[170:173], v[14:17]
	v_mfma_f32_16x16x32_bf16 v[10:13], v[154:157], v[170:173], v[10:13]
	v_mfma_f32_16x16x32_bf16 v[6:9], v[158:161], v[170:173], v[6:9]
	v_mfma_f32_16x16x32_bf16 v[2:5], v[162:165], v[170:173], v[2:5]
	s_cmpk_lg_i32 s16, 0x780
	s_waitcnt vmcnt(0)
	s_barrier
	s_cbranch_scc1 .LBB0_75
	s_add_i32 s16, 0, 0x10000
	v_add_u32_e32 v138, s16, v148
	v_readlane_b32 s16, v254, 18
	s_nop 1
	v_add_u32_e32 v139, s16, v147
	v_add_u32_e32 v145, v139, v146
	ds_read_b128 v[130:133], v145
	ds_read_b128 v[134:137], v145 offset:2048
	ds_read_b128 v[148:151], v145 offset:4096
	ds_read_b128 v[152:155], v145 offset:6144
	v_add_u32_e32 v145, v138, v146
	ds_read_b128 v[156:159], v145
	ds_read_b128 v[160:163], v145 offset:2048
	s_waitcnt lgkmcnt(1)
	v_mfma_f32_16x16x32_bf16 v[126:129], v[130:133], v[156:159], v[126:129]
	v_mfma_f32_16x16x32_bf16 v[122:125], v[134:137], v[156:159], v[122:125]
	v_mfma_f32_16x16x32_bf16 v[118:121], v[148:151], v[156:159], v[118:121]
	v_mfma_f32_16x16x32_bf16 v[114:117], v[152:155], v[156:159], v[114:117]
	ds_read_b128 v[156:159], v145 offset:4096
	s_waitcnt lgkmcnt(1)
	v_mfma_f32_16x16x32_bf16 v[110:113], v[130:133], v[160:163], v[110:113]
	v_mfma_f32_16x16x32_bf16 v[106:109], v[134:137], v[160:163], v[106:109]
	v_mfma_f32_16x16x32_bf16 v[102:105], v[148:151], v[160:163], v[102:105]
	v_mfma_f32_16x16x32_bf16 v[98:101], v[152:155], v[160:163], v[98:101]
	ds_read_b128 v[160:163], v145 offset:6144
	s_waitcnt lgkmcnt(1)
	v_mfma_f32_16x16x32_bf16 v[94:97], v[130:133], v[156:159], v[94:97]
	v_mfma_f32_16x16x32_bf16 v[90:93], v[134:137], v[156:159], v[90:93]
	v_mfma_f32_16x16x32_bf16 v[86:89], v[148:151], v[156:159], v[86:89]
	v_mfma_f32_16x16x32_bf16 v[82:85], v[152:155], v[156:159], v[82:85]
	ds_read_b128 v[156:159], v145 offset:8192
	s_waitcnt lgkmcnt(1)
	v_mfma_f32_16x16x32_bf16 v[78:81], v[130:133], v[160:163], v[78:81]
	v_mfma_f32_16x16x32_bf16 v[74:77], v[134:137], v[160:163], v[74:77]
	v_mfma_f32_16x16x32_bf16 v[70:73], v[148:151], v[160:163], v[70:73]
	v_mfma_f32_16x16x32_bf16 v[66:69], v[152:155], v[160:163], v[66:69]
	ds_read_b128 v[160:163], v145 offset:10240
	s_waitcnt lgkmcnt(1)
	v_mfma_f32_16x16x32_bf16 v[62:65], v[130:133], v[156:159], v[62:65]
	v_mfma_f32_16x16x32_bf16 v[58:61], v[134:137], v[156:159], v[58:61]
	v_mfma_f32_16x16x32_bf16 v[54:57], v[148:151], v[156:159], v[54:57]
	v_mfma_f32_16x16x32_bf16 v[50:53], v[152:155], v[156:159], v[50:53]
	ds_read_b128 v[156:159], v145 offset:12288
	s_waitcnt lgkmcnt(1)
	v_mfma_f32_16x16x32_bf16 v[46:49], v[130:133], v[160:163], v[46:49]
	v_mfma_f32_16x16x32_bf16 v[42:45], v[134:137], v[160:163], v[42:45]
	v_mfma_f32_16x16x32_bf16 v[38:41], v[148:151], v[160:163], v[38:41]
	v_mfma_f32_16x16x32_bf16 v[34:37], v[152:155], v[160:163], v[34:37]
	ds_read_b128 v[160:163], v145 offset:14336
	s_waitcnt lgkmcnt(1)
	v_mfma_f32_16x16x32_bf16 v[30:33], v[130:133], v[156:159], v[30:33]
	v_mfma_f32_16x16x32_bf16 v[26:29], v[134:137], v[156:159], v[26:29]
	v_mfma_f32_16x16x32_bf16 v[22:25], v[148:151], v[156:159], v[22:25]
	v_mfma_f32_16x16x32_bf16 v[18:21], v[152:155], v[156:159], v[18:21]
	s_waitcnt lgkmcnt(0)
	v_mfma_f32_16x16x32_bf16 v[14:17], v[130:133], v[160:163], v[14:17]
	v_mfma_f32_16x16x32_bf16 v[10:13], v[134:137], v[160:163], v[10:13]
	v_mfma_f32_16x16x32_bf16 v[6:9], v[148:151], v[160:163], v[6:9]
	v_mfma_f32_16x16x32_bf16 v[2:5], v[152:155], v[160:163], v[2:5]
	v_add_u32_e32 v139, v139, v144
	ds_read_b128 v[130:133], v139
	ds_read_b128 v[134:137], v139 offset:2048
	ds_read_b128 v[146:149], v139 offset:4096
	ds_read_b128 v[150:153], v139 offset:6144
	v_add_u32_e32 v138, v138, v144
	ds_read_b128 v[154:157], v138
	ds_read_b128 v[158:161], v138 offset:2048
	s_waitcnt lgkmcnt(1)
	v_mfma_f32_16x16x32_bf16 v[126:129], v[130:133], v[154:157], v[126:129]
	v_mfma_f32_16x16x32_bf16 v[122:125], v[134:137], v[154:157], v[122:125]
	v_mfma_f32_16x16x32_bf16 v[118:121], v[146:149], v[154:157], v[118:121]
	v_mfma_f32_16x16x32_bf16 v[114:117], v[150:153], v[154:157], v[114:117]
	ds_read_b128 v[154:157], v138 offset:4096
	s_waitcnt lgkmcnt(1)
	v_mfma_f32_16x16x32_bf16 v[162:165], v[130:133], v[158:161], v[110:113]
	v_mfma_f32_16x16x32_bf16 v[166:169], v[134:137], v[158:161], v[106:109]
	v_mfma_f32_16x16x32_bf16 v[102:105], v[146:149], v[158:161], v[102:105]
	v_mfma_f32_16x16x32_bf16 v[98:101], v[150:153], v[158:161], v[98:101]
	s_nop 0
	ds_read_b128 v[106:109], v138 offset:6144
	s_waitcnt lgkmcnt(1)
	v_mfma_f32_16x16x32_bf16 v[94:97], v[130:133], v[154:157], v[94:97]
	v_mfma_f32_16x16x32_bf16 v[90:93], v[134:137], v[154:157], v[90:93]
	v_mfma_f32_16x16x32_bf16 v[86:89], v[146:149], v[154:157], v[86:89]
	v_mfma_f32_16x16x32_bf16 v[82:85], v[150:153], v[154:157], v[82:85]
	ds_read_b128 v[110:113], v138 offset:8192
	s_waitcnt lgkmcnt(1)
; DI unsigned pack2(float a, float b) { hwf2_t f = {a, b}; return __builtin_bit_cast(unsigned, __builtin_convertvector(f, hwbf2_t)); }
; DI float fsigmoid(float x) { return __builtin_amdgcn_rcpf(1.f + __expf(-x)); }
;     ...
;   const int row0 = m0 + wm * 32 * MI + r16, cbw = n0 + wn * 64;
;   if constexpr (std::is_invocable_v<EP, int, int, int, const f32x4&, const f32x4&, const f32x4&, const f32x4&>) {
; #pragma unroll
;     for (int a = 0; a < MT; ++a) ep(row0 + 16 * a, cbw, q4, acc[a][0], acc[a][1], acc[a][2], acc[a][3]);
; DI void phase_ffn_up(char* smem, const Params& p, int layer) {
;     ...
;   auto ep = [=](int row, int cb, int q4, const f32x4& c0, const f32x4& c1, const f32x4& c2, const f32x4& c3) {
;     const uint4 o = make_uint4(pack2(c0[0] * fsigmoid(c0[0]) * c0[1], c0[2] * fsigmoid(c0[2]) * c0[3]),
;                                pack2(c1[0] * fsigmoid(c1[0]) * c1[1], c1[2] * fsigmoid(c1[2]) * c1[3]),
;                                pack2(c2[0] * fsigmoid(c2[0]) * c2[1], c2[2] * fsigmoid(c2[2]) * c2[3]),
;                                pack2(c3[0] * fsigmoid(c3[0]) * c3[1], c3[2] * fsigmoid(c3[2]) * c3[3]));
;     *(uint4*)(Hh + (size_t)row * FH + (cb >> 1) + q4 * 8) = o;
;   };
	v_mfma_f32_16x16x32_bf16 v[78:81], v[130:133], v[106:109], v[78:81]
	v_mfma_f32_16x16x32_bf16 v[74:77], v[134:137], v[106:109], v[74:77]
	v_mfma_f32_16x16x32_bf16 v[70:73], v[146:149], v[106:109], v[70:73]
	v_mfma_f32_16x16x32_bf16 v[66:69], v[150:153], v[106:109], v[66:69]
	ds_read_b128 v[106:109], v138 offset:10240
	s_waitcnt lgkmcnt(1)
	v_mfma_f32_16x16x32_bf16 v[62:65], v[130:133], v[110:113], v[62:65]
	v_mfma_f32_16x16x32_bf16 v[58:61], v[134:137], v[110:113], v[58:61]
	v_mfma_f32_16x16x32_bf16 v[54:57], v[146:149], v[110:113], v[54:57]
	v_mfma_f32_16x16x32_bf16 v[50:53], v[150:153], v[110:113], v[50:53]
	ds_read_b128 v[110:113], v138 offset:12288
	s_waitcnt lgkmcnt(1)
	v_mfma_f32_16x16x32_bf16 v[46:49], v[130:133], v[106:109], v[46:49]
	v_mfma_f32_16x16x32_bf16 v[42:45], v[134:137], v[106:109], v[42:45]
	v_mfma_f32_16x16x32_bf16 v[38:41], v[146:149], v[106:109], v[38:41]
	v_mfma_f32_16x16x32_bf16 v[34:37], v[150:153], v[106:109], v[34:37]
	ds_read_b128 v[106:109], v138 offset:14336
	s_waitcnt lgkmcnt(1)
	v_mfma_f32_16x16x32_bf16 v[30:33], v[130:133], v[110:113], v[30:33]
	v_mfma_f32_16x16x32_bf16 v[26:29], v[134:137], v[110:113], v[26:29]
	v_mfma_f32_16x16x32_bf16 v[22:25], v[146:149], v[110:113], v[22:25]
	v_mfma_f32_16x16x32_bf16 v[18:21], v[150:153], v[110:113], v[18:21]
	s_waitcnt lgkmcnt(0)
	v_mfma_f32_16x16x32_bf16 v[14:17], v[130:133], v[106:109], v[14:17]
	v_mfma_f32_16x16x32_bf16 v[10:13], v[134:137], v[106:109], v[10:13]
	v_mfma_f32_16x16x32_bf16 v[6:9], v[146:149], v[106:109], v[6:9]
	v_mfma_f32_16x16x32_bf16 v[2:5], v[150:153], v[106:109], v[2:5]
	v_or_b32_e32 v107, s38, v142
	v_lshl_add_u32 v110, v141, 7, v107
	v_mul_f32_e32 v107, 0xbfb8aa3b, v126
	v_mul_f32_e32 v108, 0xbfb8aa3b, v128
	v_exp_f32_e32 v107, v107
	v_exp_f32_e32 v109, v108
	v_lshl_or_b32 v106, v143, 6, s39
	v_ashrrev_i32_e32 v108, 1, v106
	v_add_f32_e32 v106, 1.0, v107
	v_add_f32_e32 v107, 1.0, v109
	v_rcp_f32_e32 v106, v106
	v_rcp_f32_e32 v107, v107
	v_mov_b32_e32 v112, v126
	v_mov_b32_e32 v113, v128
	v_mul_f32_e32 v111, 0xbfb8aa3b, v122
	v_pk_mul_f32 v[106:107], v[112:113], v[106:107]
	v_exp_f32_e32 v111, v111
	v_mul_f32_e32 v112, 0xbfb8aa3b, v124
	v_exp_f32_e32 v113, v112
	v_mov_b32_e32 v128, v127
	v_add_f32_e32 v111, 1.0, v111
	v_rcp_f32_e32 v112, v111
	v_add_f32_e32 v111, 1.0, v113
	v_rcp_f32_e32 v113, v111
	v_pk_mul_f32 v[106:107], v[128:129], v[106:107]
	v_mul_f32_e32 v111, 0xbfb8aa3b, v118
	v_cvt_pk_bf16_f32 v126, v106, v107
	v_mov_b32_e32 v106, v122
	v_mov_b32_e32 v107, v124
	v_pk_mul_f32 v[106:107], v[106:107], v[112:113]
	v_exp_f32_e32 v111, v111
	v_mul_f32_e32 v112, 0xbfb8aa3b, v120
	v_exp_f32_e32 v113, v112
	v_mov_b32_e32 v124, v123
	v_add_f32_e32 v111, 1.0, v111
	v_rcp_f32_e32 v112, v111
	v_add_f32_e32 v111, 1.0, v113
	v_rcp_f32_e32 v113, v111
	v_pk_mul_f32 v[106:107], v[124:125], v[106:107]
	v_mul_f32_e32 v111, 0xbfb8aa3b, v114
	v_cvt_pk_bf16_f32 v127, v106, v107
	v_mov_b32_e32 v106, v118
	v_mov_b32_e32 v107, v120
	v_pk_mul_f32 v[106:107], v[106:107], v[112:113]
	v_exp_f32_e32 v111, v111
	v_mul_f32_e32 v112, 0xbfb8aa3b, v116
	v_exp_f32_e32 v113, v112
	v_mov_b32_e32 v120, v119
	v_add_f32_e32 v111, 1.0, v111
	v_rcp_f32_e32 v112, v111
	v_add_f32_e32 v111, 1.0, v113
	v_rcp_f32_e32 v113, v111
	v_pk_mul_f32 v[106:107], v[120:121], v[106:107]
	v_readlane_b32 s52, v253, 40
	v_cvt_pk_bf16_f32 v128, v106, v107
	v_mov_b32_e32 v106, v114
	v_mov_b32_e32 v107, v116
	v_pk_mul_f32 v[106:107], v[106:107], v[112:113]
	v_mov_b32_e32 v116, v115
	v_mul_f32_e32 v111, 0xbfb8aa3b, v162
	v_pk_mul_f32 v[106:107], v[116:117], v[106:107]
	v_readlane_b32 s54, v253, 42
	v_readlane_b32 s55, v253, 43
	v_exp_f32_e32 v111, v111
	v_mul_f32_e32 v114, 0xbfb8aa3b, v164
	v_ashrrev_i32_e32 v109, 31, v108
	v_cvt_pk_bf16_f32 v129, v106, v107
	v_mov_b64_e32 v[106:107], s[54:55]
	s_movk_i32 s38, 0x1600
	v_exp_f32_e32 v114, v114
	v_mad_i64_i32 v[112:113], s[16:17], v110, s38, v[106:107]
	v_lshlrev_b64 v[108:109], 1, v[108:109]
	v_lshl_add_u64 v[112:113], v[112:113], 0, v[108:109]
	v_lshlrev_b32_e32 v190, 4, v140
	v_lshl_add_u64 v[112:113], v[112:113], 0, v[190:191]
	v_add_f32_e32 v111, 1.0, v111
	s_waitcnt vmcnt(0)
	s_barrier
	global_store_dwordx4 v[112:113], v[126:129], off
	v_rcp_f32_e32 v112, v111
	v_add_f32_e32 v111, 1.0, v114
	v_rcp_f32_e32 v113, v111
	v_mov_b32_e32 v114, v162
	v_mov_b32_e32 v115, v164
	v_mov_b32_e32 v164, v163
	v_pk_mul_f32 v[112:113], v[114:115], v[112:113]
	v_mul_f32_e32 v114, 0xbfb8aa3b, v166
	v_mul_f32_e32 v115, 0xbfb8aa3b, v168
	v_exp_f32_e32 v114, v114
	v_exp_f32_e32 v115, v115
	v_pk_mul_f32 v[112:113], v[164:165], v[112:113]
	v_mov_b32_e32 v116, v166
	v_add_f32_e32 v114, 1.0, v114
	v_add_f32_e32 v115, 1.0, v115
	v_rcp_f32_e32 v114, v114
	v_rcp_f32_e32 v115, v115
	v_cvt_pk_bf16_f32 v112, v112, v113
	v_mov_b32_e32 v117, v168
	v_mul_f32_e32 v113, 0xbfb8aa3b, v102
	v_pk_mul_f32 v[114:115], v[116:117], v[114:115]
	v_exp_f32_e32 v113, v113
	v_mul_f32_e32 v116, 0xbfb8aa3b, v104
	v_exp_f32_e32 v117, v116
	v_mov_b32_e32 v168, v167
	v_add_f32_e32 v113, 1.0, v113
	v_rcp_f32_e32 v116, v113
	v_add_f32_e32 v113, 1.0, v117
	v_rcp_f32_e32 v117, v113
	v_pk_mul_f32 v[114:115], v[168:169], v[114:115]
	v_or_b32_e32 v111, 16, v110
	v_cvt_pk_bf16_f32 v113, v114, v115
	v_mov_b32_e32 v114, v102
	v_mov_b32_e32 v115, v104
	v_mul_f32_e32 v102, 0xbfb8aa3b, v98
	v_pk_mul_f32 v[114:115], v[114:115], v[116:117]
	v_exp_f32_e32 v116, v102
	v_mul_f32_e32 v102, 0xbfb8aa3b, v100
	v_exp_f32_e32 v117, v102
	v_mov_b32_e32 v104, v103
	v_pk_mul_f32 v[102:103], v[104:105], v[114:115]
	v_add_f32_e32 v104, 1.0, v116
	v_add_f32_e32 v105, 1.0, v117
	v_rcp_f32_e32 v104, v104
	v_rcp_f32_e32 v105, v105
; DI unsigned pack2(float a, float b) { hwf2_t f = {a, b}; return __builtin_bit_cast(unsigned, __builtin_convertvector(f, hwbf2_t)); }
; DI float fsigmoid(float x) { return __builtin_amdgcn_rcpf(1.f + __expf(-x)); }
; DI void phase_ffn_up(char* smem, const Params& p, int layer) {
;     ...
;   auto ep = [=](int row, int cb, int q4, const f32x4& c0, const f32x4& c1, const f32x4& c2, const f32x4& c3) {
;     const uint4 o = make_uint4(pack2(c0[0] * fsigmoid(c0[0]) * c0[1], c0[2] * fsigmoid(c0[2]) * c0[3]),
;                                pack2(c1[0] * fsigmoid(c1[0]) * c1[1], c1[2] * fsigmoid(c1[2]) * c1[3]),
;                                pack2(c2[0] * fsigmoid(c2[0]) * c2[1], c2[2] * fsigmoid(c2[2]) * c2[3]),
;                                pack2(c3[0] * fsigmoid(c3[0]) * c3[1], c3[2] * fsigmoid(c3[2]) * c3[3]));
;     *(uint4*)(Hh + (size_t)row * FH + (cb >> 1) + q4 * 8) = o;
;   };
	v_cvt_pk_bf16_f32 v114, v102, v103
	v_mov_b32_e32 v102, v98
	v_mov_b32_e32 v103, v100
	v_pk_mul_f32 v[102:103], v[102:103], v[104:105]
	v_mov_b32_e32 v100, v99
	v_pk_mul_f32 v[98:99], v[100:101], v[102:103]
	v_mul_f32_e32 v100, 0xbfb8aa3b, v94
	v_mul_f32_e32 v101, 0xbfb8aa3b, v96
	v_exp_f32_e32 v100, v100
	v_exp_f32_e32 v101, v101
	v_cvt_pk_bf16_f32 v115, v98, v99
	v_mad_i64_i32 v[98:99], s[16:17], v111, s38, v[106:107]
	v_lshl_add_u64 v[98:99], v[98:99], 0, v[108:109]
	v_lshl_add_u64 v[98:99], v[98:99], 0, v[190:191]
	global_store_dwordx4 v[98:99], v[112:115], off
	v_add_f32_e32 v98, 1.0, v100
	v_add_f32_e32 v99, 1.0, v101
	v_rcp_f32_e32 v98, v98
	v_rcp_f32_e32 v99, v99
	v_mov_b32_e32 v100, v94
	v_mov_b32_e32 v101, v96
	v_mul_f32_e32 v94, 0xbfb8aa3b, v90
	v_pk_mul_f32 v[98:99], v[100:101], v[98:99]
	v_exp_f32_e32 v100, v94
	v_mul_f32_e32 v94, 0xbfb8aa3b, v92
	v_exp_f32_e32 v101, v94
	v_mov_b32_e32 v96, v95
	v_pk_mul_f32 v[94:95], v[96:97], v[98:99]
	v_add_f32_e32 v96, 1.0, v100
	v_add_f32_e32 v97, 1.0, v101
	v_rcp_f32_e32 v96, v96
	v_rcp_f32_e32 v97, v97
	v_mov_b32_e32 v98, v90
	v_mul_f32_e32 v90, 0xbfb8aa3b, v86
	v_cvt_pk_bf16_f32 v94, v94, v95
	v_mov_b32_e32 v99, v92
	v_exp_f32_e32 v95, v90
	v_mul_f32_e32 v90, 0xbfb8aa3b, v88
	v_pk_mul_f32 v[96:97], v[98:99], v[96:97]
	v_exp_f32_e32 v98, v90
	v_mov_b32_e32 v92, v91
	v_pk_mul_f32 v[90:91], v[92:93], v[96:97]
	v_add_f32_e32 v92, 1.0, v95
	v_add_f32_e32 v93, 1.0, v98
	v_rcp_f32_e32 v92, v92
	v_rcp_f32_e32 v93, v93
	v_cvt_pk_bf16_f32 v95, v90, v91
	v_mov_b32_e32 v90, v86
	v_mov_b32_e32 v91, v88
	v_mul_f32_e32 v86, 0xbfb8aa3b, v82
	v_pk_mul_f32 v[90:91], v[90:91], v[92:93]
	v_exp_f32_e32 v92, v86
	v_mul_f32_e32 v86, 0xbfb8aa3b, v84
	v_exp_f32_e32 v93, v86
	v_mov_b32_e32 v88, v87
	v_pk_mul_f32 v[86:87], v[88:89], v[90:91]
	v_add_f32_e32 v88, 1.0, v92
	v_add_f32_e32 v89, 1.0, v93
	v_rcp_f32_e32 v88, v88
	v_rcp_f32_e32 v89, v89
	v_cvt_pk_bf16_f32 v96, v86, v87
	v_mov_b32_e32 v86, v82
	v_mov_b32_e32 v87, v84
	v_pk_mul_f32 v[86:87], v[86:87], v[88:89]
	v_mov_b32_e32 v84, v83
	v_pk_mul_f32 v[82:83], v[84:85], v[86:87]
	v_mul_f32_e32 v84, 0xbfb8aa3b, v78
	v_mul_f32_e32 v85, 0xbfb8aa3b, v80
	v_or_b32_e32 v102, 32, v110
	v_exp_f32_e32 v84, v84
	v_exp_f32_e32 v85, v85
	v_cvt_pk_bf16_f32 v97, v82, v83
	v_mad_i64_i32 v[82:83], s[16:17], v102, s38, v[106:107]
	v_lshl_add_u64 v[82:83], v[82:83], 0, v[108:109]
	v_lshl_add_u64 v[82:83], v[82:83], 0, v[190:191]
	global_store_dwordx4 v[82:83], v[94:97], off
	v_add_f32_e32 v82, 1.0, v84
	v_add_f32_e32 v83, 1.0, v85
	v_rcp_f32_e32 v82, v82
	v_rcp_f32_e32 v83, v83
	v_mov_b32_e32 v84, v78
	v_mov_b32_e32 v85, v80
	v_mul_f32_e32 v78, 0xbfb8aa3b, v74
	v_pk_mul_f32 v[82:83], v[84:85], v[82:83]
	v_exp_f32_e32 v84, v78
	v_mul_f32_e32 v78, 0xbfb8aa3b, v76
	v_exp_f32_e32 v85, v78
	v_mov_b32_e32 v80, v79
	v_pk_mul_f32 v[78:79], v[80:81], v[82:83]
	v_add_f32_e32 v80, 1.0, v84
	v_add_f32_e32 v81, 1.0, v85
	v_rcp_f32_e32 v80, v80
	v_rcp_f32_e32 v81, v81
	v_mov_b32_e32 v82, v74
	v_mul_f32_e32 v74, 0xbfb8aa3b, v70
	v_cvt_pk_bf16_f32 v78, v78, v79
	v_mov_b32_e32 v83, v76
	v_exp_f32_e32 v79, v74
	v_mul_f32_e32 v74, 0xbfb8aa3b, v72
	v_pk_mul_f32 v[80:81], v[82:83], v[80:81]
	v_exp_f32_e32 v82, v74
	v_mov_b32_e32 v76, v75
	v_pk_mul_f32 v[74:75], v[76:77], v[80:81]
	v_add_f32_e32 v76, 1.0, v79
	v_add_f32_e32 v77, 1.0, v82
	v_rcp_f32_e32 v76, v76
	v_rcp_f32_e32 v77, v77
	v_cvt_pk_bf16_f32 v79, v74, v75
	v_mov_b32_e32 v74, v70
	v_mov_b32_e32 v75, v72
	v_mul_f32_e32 v70, 0xbfb8aa3b, v66
	v_pk_mul_f32 v[74:75], v[74:75], v[76:77]
	v_exp_f32_e32 v76, v70
	v_mul_f32_e32 v70, 0xbfb8aa3b, v68
	v_exp_f32_e32 v77, v70
	v_mov_b32_e32 v72, v71
	v_pk_mul_f32 v[70:71], v[72:73], v[74:75]
	v_add_f32_e32 v72, 1.0, v76
	v_add_f32_e32 v73, 1.0, v77
	v_rcp_f32_e32 v72, v72
	v_rcp_f32_e32 v73, v73
	v_cvt_pk_bf16_f32 v80, v70, v71
	v_mov_b32_e32 v70, v66
	v_mov_b32_e32 v71, v68
	v_pk_mul_f32 v[70:71], v[70:71], v[72:73]
	v_mov_b32_e32 v68, v67
	v_pk_mul_f32 v[66:67], v[68:69], v[70:71]
	v_mul_f32_e32 v68, 0xbfb8aa3b, v62
	v_mul_f32_e32 v69, 0xbfb8aa3b, v64
	v_or_b32_e32 v86, 48, v110
	v_exp_f32_e32 v68, v68
	v_exp_f32_e32 v69, v69
	v_cvt_pk_bf16_f32 v81, v66, v67
	v_mad_i64_i32 v[66:67], s[16:17], v86, s38, v[106:107]
	v_lshl_add_u64 v[66:67], v[66:67], 0, v[108:109]
	v_lshl_add_u64 v[66:67], v[66:67], 0, v[190:191]
	global_store_dwordx4 v[66:67], v[78:81], off
	v_add_f32_e32 v66, 1.0, v68
	v_add_f32_e32 v67, 1.0, v69
	v_rcp_f32_e32 v66, v66
	v_rcp_f32_e32 v67, v67
	v_mov_b32_e32 v68, v62
	v_mov_b32_e32 v69, v64
	v_mul_f32_e32 v62, 0xbfb8aa3b, v58
	v_pk_mul_f32 v[66:67], v[68:69], v[66:67]
	v_exp_f32_e32 v68, v62
	v_mul_f32_e32 v62, 0xbfb8aa3b, v60
	v_exp_f32_e32 v69, v62
	v_mov_b32_e32 v64, v63
	v_pk_mul_f32 v[62:63], v[64:65], v[66:67]
	v_add_f32_e32 v64, 1.0, v68
	v_add_f32_e32 v65, 1.0, v69
	v_rcp_f32_e32 v64, v64
	v_rcp_f32_e32 v65, v65
	v_mov_b32_e32 v66, v58
	v_mul_f32_e32 v58, 0xbfb8aa3b, v54
	v_cvt_pk_bf16_f32 v62, v62, v63
	v_mov_b32_e32 v67, v60
	v_exp_f32_e32 v63, v58
	v_mul_f32_e32 v58, 0xbfb8aa3b, v56
	v_pk_mul_f32 v[64:65], v[66:67], v[64:65]
	v_exp_f32_e32 v66, v58
	v_mov_b32_e32 v60, v59
	v_pk_mul_f32 v[58:59], v[60:61], v[64:65]
	v_add_f32_e32 v60, 1.0, v63
	v_add_f32_e32 v61, 1.0, v66
	v_rcp_f32_e32 v60, v60
	v_rcp_f32_e32 v61, v61
	v_cvt_pk_bf16_f32 v63, v58, v59
	v_mov_b32_e32 v58, v54
	v_mov_b32_e32 v59, v56
	v_mul_f32_e32 v54, 0xbfb8aa3b, v50
	v_pk_mul_f32 v[58:59], v[58:59], v[60:61]
	v_exp_f32_e32 v60, v54
	v_mul_f32_e32 v54, 0xbfb8aa3b, v52
	v_exp_f32_e32 v61, v54
	v_mov_b32_e32 v56, v55
	v_pk_mul_f32 v[54:55], v[56:57], v[58:59]
	v_add_f32_e32 v56, 1.0, v60
; DI unsigned pack2(float a, float b) { hwf2_t f = {a, b}; return __builtin_bit_cast(unsigned, __builtin_convertvector(f, hwbf2_t)); }
; DI float fsigmoid(float x) { return __builtin_amdgcn_rcpf(1.f + __expf(-x)); }
; DI void phase_ffn_up(char* smem, const Params& p, int layer) {
;     ...
;   auto ep = [=](int row, int cb, int q4, const f32x4& c0, const f32x4& c1, const f32x4& c2, const f32x4& c3) {
;     const uint4 o = make_uint4(pack2(c0[0] * fsigmoid(c0[0]) * c0[1], c0[2] * fsigmoid(c0[2]) * c0[3]),
;                                pack2(c1[0] * fsigmoid(c1[0]) * c1[1], c1[2] * fsigmoid(c1[2]) * c1[3]),
;                                pack2(c2[0] * fsigmoid(c2[0]) * c2[1], c2[2] * fsigmoid(c2[2]) * c2[3]),
;                                pack2(c3[0] * fsigmoid(c3[0]) * c3[1], c3[2] * fsigmoid(c3[2]) * c3[3]));
;     *(uint4*)(Hh + (size_t)row * FH + (cb >> 1) + q4 * 8) = o;
;   };
	v_add_f32_e32 v57, 1.0, v61
	v_rcp_f32_e32 v56, v56
	v_rcp_f32_e32 v57, v57
	v_cvt_pk_bf16_f32 v64, v54, v55
	v_mov_b32_e32 v54, v50
	v_mov_b32_e32 v55, v52
	v_pk_mul_f32 v[54:55], v[54:55], v[56:57]
	v_mov_b32_e32 v52, v51
	v_pk_mul_f32 v[50:51], v[52:53], v[54:55]
	v_mul_f32_e32 v52, 0xbfb8aa3b, v46
	v_mul_f32_e32 v53, 0xbfb8aa3b, v48
	v_or_b32_e32 v70, 64, v110
	v_exp_f32_e32 v52, v52
	v_exp_f32_e32 v53, v53
	v_cvt_pk_bf16_f32 v65, v50, v51
	v_mad_i64_i32 v[50:51], s[16:17], v70, s38, v[106:107]
	v_lshl_add_u64 v[50:51], v[50:51], 0, v[108:109]
	v_lshl_add_u64 v[50:51], v[50:51], 0, v[190:191]
	global_store_dwordx4 v[50:51], v[62:65], off
	v_add_f32_e32 v50, 1.0, v52
	v_add_f32_e32 v51, 1.0, v53
	v_rcp_f32_e32 v50, v50
	v_rcp_f32_e32 v51, v51
	v_mov_b32_e32 v52, v46
	v_mov_b32_e32 v53, v48
	v_mul_f32_e32 v46, 0xbfb8aa3b, v42
	v_pk_mul_f32 v[50:51], v[52:53], v[50:51]
	v_exp_f32_e32 v52, v46
	v_mul_f32_e32 v46, 0xbfb8aa3b, v44
	v_exp_f32_e32 v53, v46
	v_mov_b32_e32 v48, v47
	v_pk_mul_f32 v[46:47], v[48:49], v[50:51]
	v_add_f32_e32 v48, 1.0, v52
	v_add_f32_e32 v49, 1.0, v53
	v_rcp_f32_e32 v48, v48
	v_rcp_f32_e32 v49, v49
	v_mov_b32_e32 v50, v42
	v_mul_f32_e32 v42, 0xbfb8aa3b, v38
	v_cvt_pk_bf16_f32 v46, v46, v47
	v_mov_b32_e32 v51, v44
	v_exp_f32_e32 v47, v42
	v_mul_f32_e32 v42, 0xbfb8aa3b, v40
	v_pk_mul_f32 v[48:49], v[50:51], v[48:49]
	v_exp_f32_e32 v50, v42
	v_mov_b32_e32 v44, v43
	v_pk_mul_f32 v[42:43], v[44:45], v[48:49]
	v_add_f32_e32 v44, 1.0, v47
	v_add_f32_e32 v45, 1.0, v50
	v_rcp_f32_e32 v44, v44
	v_rcp_f32_e32 v45, v45
	v_cvt_pk_bf16_f32 v47, v42, v43
	v_mov_b32_e32 v42, v38
	v_mov_b32_e32 v43, v40
	v_mul_f32_e32 v38, 0xbfb8aa3b, v34
	v_pk_mul_f32 v[42:43], v[42:43], v[44:45]
	v_exp_f32_e32 v44, v38
	v_mul_f32_e32 v38, 0xbfb8aa3b, v36
	v_exp_f32_e32 v45, v38
	v_mov_b32_e32 v40, v39
	v_pk_mul_f32 v[38:39], v[40:41], v[42:43]
	v_add_f32_e32 v40, 1.0, v44
	v_add_f32_e32 v41, 1.0, v45
	v_rcp_f32_e32 v40, v40
	v_rcp_f32_e32 v41, v41
	v_cvt_pk_bf16_f32 v48, v38, v39
	v_mov_b32_e32 v38, v34
	v_mov_b32_e32 v39, v36
	v_pk_mul_f32 v[38:39], v[38:39], v[40:41]
	v_mov_b32_e32 v36, v35
	v_pk_mul_f32 v[34:35], v[36:37], v[38:39]
	v_mul_f32_e32 v36, 0xbfb8aa3b, v30
	v_mul_f32_e32 v37, 0xbfb8aa3b, v32
	v_or_b32_e32 v54, 0x50, v110
	v_exp_f32_e32 v36, v36
	v_exp_f32_e32 v37, v37
	v_cvt_pk_bf16_f32 v49, v34, v35
	v_mad_i64_i32 v[34:35], s[16:17], v54, s38, v[106:107]
	v_lshl_add_u64 v[34:35], v[34:35], 0, v[108:109]
	v_lshl_add_u64 v[34:35], v[34:35], 0, v[190:191]
	global_store_dwordx4 v[34:35], v[46:49], off
	v_add_f32_e32 v34, 1.0, v36
	v_add_f32_e32 v35, 1.0, v37
	v_rcp_f32_e32 v34, v34
	v_rcp_f32_e32 v35, v35
	v_mov_b32_e32 v36, v30
	v_mov_b32_e32 v37, v32
	v_mul_f32_e32 v30, 0xbfb8aa3b, v26
	v_pk_mul_f32 v[34:35], v[36:37], v[34:35]
	v_exp_f32_e32 v36, v30
	v_mul_f32_e32 v30, 0xbfb8aa3b, v28
	v_exp_f32_e32 v37, v30
	v_mov_b32_e32 v32, v31
	v_pk_mul_f32 v[30:31], v[32:33], v[34:35]
	v_add_f32_e32 v32, 1.0, v36
	v_add_f32_e32 v33, 1.0, v37
	v_rcp_f32_e32 v32, v32
	v_rcp_f32_e32 v33, v33
	v_mov_b32_e32 v34, v26
	v_mul_f32_e32 v26, 0xbfb8aa3b, v22
	v_cvt_pk_bf16_f32 v30, v30, v31
	v_mov_b32_e32 v35, v28
	v_exp_f32_e32 v31, v26
	v_mul_f32_e32 v26, 0xbfb8aa3b, v24
	v_pk_mul_f32 v[32:33], v[34:35], v[32:33]
	v_exp_f32_e32 v34, v26
	v_mov_b32_e32 v28, v27
	v_pk_mul_f32 v[26:27], v[28:29], v[32:33]
	v_add_f32_e32 v28, 1.0, v31
	v_add_f32_e32 v29, 1.0, v34
	v_rcp_f32_e32 v28, v28
	v_rcp_f32_e32 v29, v29
	v_cvt_pk_bf16_f32 v31, v26, v27
	v_mov_b32_e32 v26, v22
	v_mov_b32_e32 v27, v24
	v_mul_f32_e32 v22, 0xbfb8aa3b, v18
	v_pk_mul_f32 v[26:27], v[26:27], v[28:29]
	v_exp_f32_e32 v28, v22
	v_mul_f32_e32 v22, 0xbfb8aa3b, v20
	v_exp_f32_e32 v29, v22
	v_mov_b32_e32 v24, v23
	v_pk_mul_f32 v[22:23], v[24:25], v[26:27]
	v_add_f32_e32 v24, 1.0, v28
	v_add_f32_e32 v25, 1.0, v29
	v_rcp_f32_e32 v24, v24
	v_rcp_f32_e32 v25, v25
	v_cvt_pk_bf16_f32 v32, v22, v23
	v_mov_b32_e32 v22, v18
	v_mov_b32_e32 v23, v20
	v_pk_mul_f32 v[22:23], v[22:23], v[24:25]
	v_mov_b32_e32 v20, v19
	v_pk_mul_f32 v[18:19], v[20:21], v[22:23]
	v_mul_f32_e32 v20, 0xbfb8aa3b, v14
	v_mul_f32_e32 v21, 0xbfb8aa3b, v16
	v_or_b32_e32 v38, 0x60, v110
	v_exp_f32_e32 v20, v20
	v_exp_f32_e32 v21, v21
	v_cvt_pk_bf16_f32 v33, v18, v19
	v_mad_i64_i32 v[18:19], s[16:17], v38, s38, v[106:107]
	v_lshl_add_u64 v[18:19], v[18:19], 0, v[108:109]
	v_lshl_add_u64 v[18:19], v[18:19], 0, v[190:191]
	global_store_dwordx4 v[18:19], v[30:33], off
	v_add_f32_e32 v18, 1.0, v20
	v_add_f32_e32 v19, 1.0, v21
	v_rcp_f32_e32 v18, v18
	v_rcp_f32_e32 v19, v19
	v_mov_b32_e32 v20, v14
	v_mov_b32_e32 v21, v16
	v_mul_f32_e32 v14, 0xbfb8aa3b, v10
	v_pk_mul_f32 v[18:19], v[20:21], v[18:19]
	v_exp_f32_e32 v20, v14
	v_mul_f32_e32 v14, 0xbfb8aa3b, v12
	v_exp_f32_e32 v21, v14
	v_mov_b32_e32 v16, v15
	v_pk_mul_f32 v[14:15], v[16:17], v[18:19]
	v_add_f32_e32 v16, 1.0, v20
	v_add_f32_e32 v17, 1.0, v21
	v_rcp_f32_e32 v16, v16
	v_rcp_f32_e32 v17, v17
	v_mov_b32_e32 v18, v10
	v_mul_f32_e32 v10, 0xbfb8aa3b, v6
	v_cvt_pk_bf16_f32 v14, v14, v15
	v_mov_b32_e32 v19, v12
	v_exp_f32_e32 v15, v10
	v_mul_f32_e32 v10, 0xbfb8aa3b, v8
	v_pk_mul_f32 v[16:17], v[18:19], v[16:17]
	v_exp_f32_e32 v18, v10
	v_mov_b32_e32 v12, v11
	v_pk_mul_f32 v[10:11], v[12:13], v[16:17]
	v_add_f32_e32 v12, 1.0, v15
	v_add_f32_e32 v13, 1.0, v18
	v_rcp_f32_e32 v12, v12
	v_rcp_f32_e32 v13, v13
	v_cvt_pk_bf16_f32 v15, v10, v11
	v_mov_b32_e32 v10, v6
	v_mov_b32_e32 v11, v8
	v_mul_f32_e32 v6, 0xbfb8aa3b, v2
	v_pk_mul_f32 v[10:11], v[10:11], v[12:13]
	v_exp_f32_e32 v12, v6
	v_mul_f32_e32 v6, 0xbfb8aa3b, v4
	v_exp_f32_e32 v13, v6
	v_mov_b32_e32 v8, v7
	v_pk_mul_f32 v[6:7], v[8:9], v[10:11]
	v_add_f32_e32 v8, 1.0, v12
	v_add_f32_e32 v9, 1.0, v13
	v_rcp_f32_e32 v8, v8
	v_rcp_f32_e32 v9, v9
	v_cvt_pk_bf16_f32 v16, v6, v7
	v_mov_b32_e32 v6, v2
	v_mov_b32_e32 v7, v4
	v_pk_mul_f32 v[6:7], v[6:7], v[8:9]
	v_mov_b32_e32 v4, v3
	v_or_b32_e32 v22, 0x70, v110
	v_pk_mul_f32 v[2:3], v[4:5], v[6:7]
	s_add_i32 s37, s37, s30
	v_cvt_pk_bf16_f32 v17, v2, v3
	v_mad_i64_i32 v[2:3], s[16:17], v22, s38, v[106:107]
	v_lshl_add_u64 v[2:3], v[2:3], 0, v[108:109]
	s_cmp_gt_i32 s37, 31
	v_lshl_add_u64 v[2:3], v[2:3], 0, v[190:191]
	s_cselect_b64 s[16:17], -1, 0
	v_readlane_b32 s53, v253, 41
	v_readlane_b32 s56, v253, 44
	v_readlane_b32 s57, v253, 45
	v_readlane_b32 s58, v253, 46
	v_readlane_b32 s59, v253, 47
	v_readlane_b32 s60, v253, 48
	v_readlane_b32 s61, v253, 49
	v_readlane_b32 s62, v253, 50
	v_readlane_b32 s63, v253, 51
	v_readlane_b32 s64, v253, 52
	v_readlane_b32 s65, v253, 53
	v_readlane_b32 s66, v253, 54
	v_readlane_b32 s67, v253, 55
	global_store_dwordx4 v[2:3], v[14:17], off
	s_branch .LBB0_68

; #define MFMA16(a, b, c) __builtin_amdgcn_mfma_f32_16x16x32_bf16((a), (b), (c), 0, 0, 0)
;     ...
;   for (int kt = 0; kt < nk; ++kt) {
;     const int buf = kt & 1;
;     const char* cA = smem + buf * STAGE + (wm * 32 * MI + r16) * 128;
;     const char* cB = smem + buf * STAGE + 32768 + (wn * 64 + r16) * 128;
; #pragma unroll
;     for (int k2 = 0; k2 < 2; ++k2) {
;       if (k2 == 1 && kt + 1 < nk) STAGE_TILE(buf ^ 1, (kt + 1) * 64)
;       const int po = ((4 * k2 + q4) ^ swz) * 16;
;       bf16x8 bf[4];
; #pragma unroll
;       for (int nt = 0; nt < 4; ++nt) bf[nt] = *(const bf16x8*)(cB + nt * 16 * 128 + po);
;       bf16x8 afc = *(const bf16x8*)(cA + po);
; #pragma unroll
;       for (int a = 0; a < MT; ++a) {
;         bf16x8 afn = afc;
;         if (a + 1 < MT) afn = *(const bf16x8*)(cA + (a + 1) * 16 * 128 + po);
;         __builtin_amdgcn_sched_barrier(0);
; #pragma unroll
;         for (int nt = 0; nt < 4; ++nt) acc[a][nt] = MFMA16(bf[nt], afc, acc[a][nt]);
;         __builtin_amdgcn_sched_barrier(0);
;         afc = afn;
;       }
;     }
.LBB0_107:
	s_and_b32 s46, s45, 0x10000
	s_add_i32 s47, s46, 0
	s_xor_b32 s46, s46, 0x10000
	v_add_u32_e32 v174, s47, v147
	v_add_u32_e32 v162, v174, v146
	v_add_u32_e32 v149, s47, v148
	v_add_u32_e32 v175, v149, v146
	ds_read_b128 v[150:153], v162 offset:32768
	ds_read_b128 v[166:169], v175
	ds_read_b128 v[154:157], v162 offset:34816
	ds_read_b128 v[158:161], v162 offset:36864
	ds_read_b128 v[162:165], v162 offset:38912
	ds_read_b128 v[170:173], v175 offset:2048
	ds_read_b128 v[184:187], v175 offset:4096
	s_waitcnt lgkmcnt(5)
	v_mfma_f32_16x16x32_bf16 v[126:129], v[150:153], v[166:169], v[126:129]
	v_readfirstlane_b32 s47, v145
	s_waitcnt lgkmcnt(4)
	v_mfma_f32_16x16x32_bf16 v[122:125], v[154:157], v[166:169], v[122:125]
	s_nop 0
	s_waitcnt lgkmcnt(3)
	v_mfma_f32_16x16x32_bf16 v[118:121], v[158:161], v[166:169], v[118:121]
	s_add_u32 s47, s47, s46
	s_waitcnt lgkmcnt(2)
	v_mfma_f32_16x16x32_bf16 v[114:117], v[162:165], v[166:169], v[114:117]
	ds_read_b128 v[166:169], v175 offset:6144
	s_waitcnt lgkmcnt(2)
	v_mfma_f32_16x16x32_bf16 v[110:113], v[150:153], v[170:173], v[110:113]
	s_add_u32 m0, s47, 0x0
	v_mfma_f32_16x16x32_bf16 v[106:109], v[154:157], v[170:173], v[106:109]
	global_load_lds_dwordx4 v176, s[100:101]
	v_mfma_f32_16x16x32_bf16 v[102:105], v[158:161], v[170:173], v[102:105]
	s_add_u32 m0, s47, 0x2000
	v_mfma_f32_16x16x32_bf16 v[98:101], v[162:165], v[170:173], v[98:101]
	ds_read_b128 v[170:173], v175 offset:8192
	s_waitcnt lgkmcnt(2)
	v_mfma_f32_16x16x32_bf16 v[94:97], v[150:153], v[184:187], v[94:97]
	global_load_lds_dwordx4 v177, s[100:101]
	v_mfma_f32_16x16x32_bf16 v[90:93], v[154:157], v[184:187], v[90:93]
	s_add_u32 m0, s47, 0x4000
	v_mfma_f32_16x16x32_bf16 v[86:89], v[158:161], v[184:187], v[86:89]
	global_load_lds_dwordx4 v178, s[100:101]
	v_mfma_f32_16x16x32_bf16 v[82:85], v[162:165], v[184:187], v[82:85]
	ds_read_b128 v[184:187], v175 offset:10240
	s_waitcnt lgkmcnt(2)
	v_mfma_f32_16x16x32_bf16 v[78:81], v[150:153], v[166:169], v[78:81]
	s_add_u32 m0, s47, 0x6000
	v_mfma_f32_16x16x32_bf16 v[74:77], v[154:157], v[166:169], v[74:77]
	global_load_lds_dwordx4 v179, s[100:101]
	v_mfma_f32_16x16x32_bf16 v[70:73], v[158:161], v[166:169], v[70:73]
	s_add_u32 m0, s47, 0x8000
	v_mfma_f32_16x16x32_bf16 v[66:69], v[162:165], v[166:169], v[66:69]
	ds_read_b128 v[166:169], v175 offset:12288
	s_waitcnt lgkmcnt(2)
	v_mfma_f32_16x16x32_bf16 v[62:65], v[150:153], v[170:173], v[62:65]
	global_load_lds_dwordx4 v180, s[100:101]
	v_mfma_f32_16x16x32_bf16 v[58:61], v[154:157], v[170:173], v[58:61]
	s_add_u32 m0, s47, 0xa000
	v_mfma_f32_16x16x32_bf16 v[54:57], v[158:161], v[170:173], v[54:57]
	global_load_lds_dwordx4 v181, s[100:101]
	v_mfma_f32_16x16x32_bf16 v[50:53], v[162:165], v[170:173], v[50:53]
	ds_read_b128 v[170:173], v175 offset:14336
	s_waitcnt lgkmcnt(2)
	v_mfma_f32_16x16x32_bf16 v[46:49], v[150:153], v[184:187], v[46:49]
	s_add_u32 m0, s47, 0xc000
	v_mfma_f32_16x16x32_bf16 v[42:45], v[154:157], v[184:187], v[42:45]
	global_load_lds_dwordx4 v182, s[100:101]
	v_mfma_f32_16x16x32_bf16 v[38:41], v[158:161], v[184:187], v[38:41]
	s_add_u32 m0, s47, 0xe000
	v_mfma_f32_16x16x32_bf16 v[34:37], v[162:165], v[184:187], v[34:37]
	s_waitcnt lgkmcnt(1)
	v_mfma_f32_16x16x32_bf16 v[30:33], v[150:153], v[166:169], v[30:33]
	global_load_lds_dwordx4 v183, s[100:101]
	v_mfma_f32_16x16x32_bf16 v[26:29], v[154:157], v[166:169], v[26:29]
	v_mfma_f32_16x16x32_bf16 v[22:25], v[158:161], v[166:169], v[22:25]
	v_mfma_f32_16x16x32_bf16 v[18:21], v[162:165], v[166:169], v[18:21]
	s_waitcnt lgkmcnt(0)
; #define MFMA16(a, b, c) __builtin_amdgcn_mfma_f32_16x16x32_bf16((a), (b), (c), 0, 0, 0)
;     ...
;   for (int kt = 0; kt < nk; ++kt) {
;     const int buf = kt & 1;
;     const char* cA = smem + buf * STAGE + (wm * 32 * MI + r16) * 128;
;     const char* cB = smem + buf * STAGE + 32768 + (wn * 64 + r16) * 128;
; #pragma unroll
;     for (int k2 = 0; k2 < 2; ++k2) {
;       if (k2 == 1 && kt + 1 < nk) STAGE_TILE(buf ^ 1, (kt + 1) * 64)
;       const int po = ((4 * k2 + q4) ^ swz) * 16;
;       bf16x8 bf[4];
; #pragma unroll
;       for (int nt = 0; nt < 4; ++nt) bf[nt] = *(const bf16x8*)(cB + nt * 16 * 128 + po);
;       bf16x8 afc = *(const bf16x8*)(cA + po);
; #pragma unroll
;       for (int a = 0; a < MT; ++a) {
;         bf16x8 afn = afc;
;         if (a + 1 < MT) afn = *(const bf16x8*)(cA + (a + 1) * 16 * 128 + po);
;         __builtin_amdgcn_sched_barrier(0);
; #pragma unroll
;         for (int nt = 0; nt < 4; ++nt) acc[a][nt] = MFMA16(bf[nt], afc, acc[a][nt]);
;         __builtin_amdgcn_sched_barrier(0);
;         afc = afn;
;       }
;     }
;     asm volatile("s_waitcnt vmcnt(0)" ::: "memory");
;     __syncthreads();
;   }
	v_mfma_f32_16x16x32_bf16 v[14:17], v[150:153], v[170:173], v[14:17]
	v_mfma_f32_16x16x32_bf16 v[10:13], v[154:157], v[170:173], v[10:13]
	v_mfma_f32_16x16x32_bf16 v[6:9], v[158:161], v[170:173], v[6:9]
	v_mfma_f32_16x16x32_bf16 v[2:5], v[162:165], v[170:173], v[2:5]
	v_add_u32_e32 v162, v174, v144
	v_add_u32_e32 v149, v149, v144
	ds_read_b128 v[150:153], v162 offset:32768
	ds_read_b128 v[166:169], v149
	ds_read_b128 v[154:157], v162 offset:34816
	ds_read_b128 v[158:161], v162 offset:36864
	ds_read_b128 v[162:165], v162 offset:38912
	ds_read_b128 v[170:173], v149 offset:2048
	ds_read_b128 v[184:187], v149 offset:4096
	s_waitcnt lgkmcnt(5)
	v_mfma_f32_16x16x32_bf16 v[126:129], v[150:153], v[166:169], v[126:129]
	s_add_u32 s100, s100, 0x80
	s_waitcnt lgkmcnt(4)
	v_mfma_f32_16x16x32_bf16 v[122:125], v[154:157], v[166:169], v[122:125]
	s_addc_u32 s101, s101, 0
	s_waitcnt lgkmcnt(3)
	v_mfma_f32_16x16x32_bf16 v[118:121], v[158:161], v[166:169], v[118:121]
	s_add_u32 s22, s22, 0x80
	s_waitcnt lgkmcnt(2)
	v_mfma_f32_16x16x32_bf16 v[114:117], v[162:165], v[166:169], v[114:117]
	ds_read_b128 v[166:169], v149 offset:6144
	s_waitcnt lgkmcnt(2)
	v_mfma_f32_16x16x32_bf16 v[110:113], v[150:153], v[170:173], v[110:113]
	s_addc_u32 s23, s23, 0
	v_mfma_f32_16x16x32_bf16 v[106:109], v[154:157], v[170:173], v[106:109]
	s_add_i32 s45, s45, 0x10000
	v_mfma_f32_16x16x32_bf16 v[102:105], v[158:161], v[170:173], v[102:105]
	v_mfma_f32_16x16x32_bf16 v[98:101], v[162:165], v[170:173], v[98:101]
	ds_read_b128 v[170:173], v149 offset:8192
	s_waitcnt lgkmcnt(2)
	v_mfma_f32_16x16x32_bf16 v[94:97], v[150:153], v[184:187], v[94:97]
	v_mfma_f32_16x16x32_bf16 v[90:93], v[154:157], v[184:187], v[90:93]
	v_mfma_f32_16x16x32_bf16 v[86:89], v[158:161], v[184:187], v[86:89]
	v_mfma_f32_16x16x32_bf16 v[82:85], v[162:165], v[184:187], v[82:85]
	ds_read_b128 v[184:187], v149 offset:10240
	s_waitcnt lgkmcnt(2)
	v_mfma_f32_16x16x32_bf16 v[78:81], v[150:153], v[166:169], v[78:81]
	v_mfma_f32_16x16x32_bf16 v[74:77], v[154:157], v[166:169], v[74:77]
	v_mfma_f32_16x16x32_bf16 v[70:73], v[158:161], v[166:169], v[70:73]
	v_mfma_f32_16x16x32_bf16 v[66:69], v[162:165], v[166:169], v[66:69]
	ds_read_b128 v[166:169], v149 offset:12288
	s_waitcnt lgkmcnt(2)
	v_mfma_f32_16x16x32_bf16 v[62:65], v[150:153], v[170:173], v[62:65]
	v_mfma_f32_16x16x32_bf16 v[58:61], v[154:157], v[170:173], v[58:61]
	v_mfma_f32_16x16x32_bf16 v[54:57], v[158:161], v[170:173], v[54:57]
	v_mfma_f32_16x16x32_bf16 v[50:53], v[162:165], v[170:173], v[50:53]
	ds_read_b128 v[170:173], v149 offset:14336
	s_waitcnt lgkmcnt(2)
	v_mfma_f32_16x16x32_bf16 v[46:49], v[150:153], v[184:187], v[46:49]
	v_mfma_f32_16x16x32_bf16 v[42:45], v[154:157], v[184:187], v[42:45]
	v_mfma_f32_16x16x32_bf16 v[38:41], v[158:161], v[184:187], v[38:41]
	v_mfma_f32_16x16x32_bf16 v[34:37], v[162:165], v[184:187], v[34:37]
	s_waitcnt lgkmcnt(1)
	v_mfma_f32_16x16x32_bf16 v[30:33], v[150:153], v[166:169], v[30:33]
	v_mfma_f32_16x16x32_bf16 v[26:29], v[154:157], v[166:169], v[26:29]
	v_mfma_f32_16x16x32_bf16 v[22:25], v[158:161], v[166:169], v[22:25]
	v_mfma_f32_16x16x32_bf16 v[18:21], v[162:165], v[166:169], v[18:21]
	s_waitcnt lgkmcnt(0)
	v_mfma_f32_16x16x32_bf16 v[14:17], v[150:153], v[170:173], v[14:17]
	v_mfma_f32_16x16x32_bf16 v[10:13], v[154:157], v[170:173], v[10:13]
	v_mfma_f32_16x16x32_bf16 v[6:9], v[158:161], v[170:173], v[6:9]
	v_mfma_f32_16x16x32_bf16 v[2:5], v[162:165], v[170:173], v[2:5]
	s_cmpk_eq_i32 s22, 0x780
	s_waitcnt vmcnt(0)
	s_barrier
	s_cbranch_scc0 .LBB0_107
	s_branch .LBB0_99

; #define MFMA16(a, b, c) __builtin_amdgcn_mfma_f32_16x16x32_bf16((a), (b), (c), 0, 0, 0)
;     ...
;   for (int kt = 0; kt < nk; ++kt) {
;     const int buf = kt & 1;
;     const char* cA = smem + buf * STAGE + (wm * 32 * MI + r16) * 128;
;     const char* cB = smem + buf * STAGE + 32768 + (wn * 64 + r16) * 128;
; #pragma unroll
;     for (int k2 = 0; k2 < 2; ++k2) {
;       if (k2 == 1 && kt + 1 < nk) STAGE_TILE(buf ^ 1, (kt + 1) * 64)
;       const int po = ((4 * k2 + q4) ^ swz) * 16;
;       bf16x8 bf[4];
; #pragma unroll
;       for (int nt = 0; nt < 4; ++nt) bf[nt] = *(const bf16x8*)(cB + nt * 16 * 128 + po);
;       bf16x8 afc = *(const bf16x8*)(cA + po);
; #pragma unroll
;       for (int a = 0; a < MT; ++a) {
;         bf16x8 afn = afc;
;         if (a + 1 < MT) afn = *(const bf16x8*)(cA + (a + 1) * 16 * 128 + po);
;         __builtin_amdgcn_sched_barrier(0);
; #pragma unroll
;         for (int nt = 0; nt < 4; ++nt) acc[a][nt] = MFMA16(bf[nt], afc, acc[a][nt]);
;         __builtin_amdgcn_sched_barrier(0);
;         afc = afn;
;       }
;     }
;     asm volatile("s_waitcnt vmcnt(0)" ::: "memory");
;     __syncthreads();
;   }
.LBB0_565:
	s_and_b32 s6, s5, 0x10000
	s_add_i32 s7, s6, 0
	v_add_u32_e32 v190, s7, v146
	v_add_u32_e32 v164, v190, v145
	v_add_u32_e32 v163, s7, v147
	v_add_u32_e32 v202, v163, v145
	s_xor_b32 s6, s6, 0x10000
	ds_read_b128 v[148:151], v164 offset:32768
	ds_read_b128 v[168:171], v202
	ds_read_b128 v[152:155], v164 offset:34816
	ds_read_b128 v[156:159], v164 offset:36864
	ds_read_b128 v[164:167], v164 offset:38912
	ds_read_b128 v[172:175], v202 offset:2048
	ds_read_b128 v[184:187], v202 offset:4096
	s_waitcnt lgkmcnt(5)
	v_mfma_f32_16x16x32_bf16 v[126:129], v[148:151], v[168:171], v[126:129]
	v_readfirstlane_b32 s7, v144
	s_waitcnt lgkmcnt(4)
	v_mfma_f32_16x16x32_bf16 v[122:125], v[152:155], v[168:171], v[122:125]
	s_nop 0
	s_waitcnt lgkmcnt(3)
	v_mfma_f32_16x16x32_bf16 v[118:121], v[156:159], v[168:171], v[118:121]
	s_add_u32 s7, s7, s6
	s_waitcnt lgkmcnt(2)
	v_mfma_f32_16x16x32_bf16 v[114:117], v[164:167], v[168:171], v[114:117]
	ds_read_b128 v[168:171], v202 offset:6144
	s_waitcnt lgkmcnt(2)
	v_mfma_f32_16x16x32_bf16 v[110:113], v[148:151], v[172:175], v[110:113]
	s_add_u32 m0, s7, 0x0
	v_mfma_f32_16x16x32_bf16 v[106:109], v[152:155], v[172:175], v[106:109]
	global_load_lds_dwordx4 v176, s[100:101]
	v_mfma_f32_16x16x32_bf16 v[102:105], v[156:159], v[172:175], v[102:105]
	s_add_u32 m0, s7, 0x2000
	v_mfma_f32_16x16x32_bf16 v[98:101], v[164:167], v[172:175], v[98:101]
	ds_read_b128 v[172:175], v202 offset:8192
	s_waitcnt lgkmcnt(2)
	v_mfma_f32_16x16x32_bf16 v[94:97], v[148:151], v[184:187], v[94:97]
	global_load_lds_dwordx4 v177, s[100:101]
	v_mfma_f32_16x16x32_bf16 v[90:93], v[152:155], v[184:187], v[90:93]
	s_add_u32 m0, s7, 0x4000
	v_mfma_f32_16x16x32_bf16 v[86:89], v[156:159], v[184:187], v[86:89]
	global_load_lds_dwordx4 v178, s[100:101]
	v_mfma_f32_16x16x32_bf16 v[82:85], v[164:167], v[184:187], v[82:85]
	ds_read_b128 v[184:187], v202 offset:10240
	s_waitcnt lgkmcnt(2)
	v_mfma_f32_16x16x32_bf16 v[78:81], v[148:151], v[168:171], v[78:81]
	s_add_u32 m0, s7, 0x6000
	v_mfma_f32_16x16x32_bf16 v[74:77], v[152:155], v[168:171], v[74:77]
	global_load_lds_dwordx4 v179, s[100:101]
	v_mfma_f32_16x16x32_bf16 v[70:73], v[156:159], v[168:171], v[70:73]
	s_add_u32 m0, s7, 0x8000
	v_mfma_f32_16x16x32_bf16 v[66:69], v[164:167], v[168:171], v[66:69]
	ds_read_b128 v[168:171], v202 offset:12288
	s_waitcnt lgkmcnt(2)
	v_mfma_f32_16x16x32_bf16 v[62:65], v[148:151], v[172:175], v[62:65]
	global_load_lds_dwordx4 v180, s[100:101]
	v_mfma_f32_16x16x32_bf16 v[58:61], v[152:155], v[172:175], v[58:61]
	s_add_u32 m0, s7, 0xa000
	v_mfma_f32_16x16x32_bf16 v[54:57], v[156:159], v[172:175], v[54:57]
	global_load_lds_dwordx4 v181, s[100:101]
	v_mfma_f32_16x16x32_bf16 v[50:53], v[164:167], v[172:175], v[50:53]
	ds_read_b128 v[172:175], v202 offset:14336
	s_waitcnt lgkmcnt(2)
	v_mfma_f32_16x16x32_bf16 v[46:49], v[148:151], v[184:187], v[46:49]
	s_add_u32 m0, s7, 0xc000
	v_mfma_f32_16x16x32_bf16 v[42:45], v[152:155], v[184:187], v[42:45]
	global_load_lds_dwordx4 v182, s[100:101]
	v_mfma_f32_16x16x32_bf16 v[38:41], v[156:159], v[184:187], v[38:41]
	s_add_u32 m0, s7, 0xe000
	v_mfma_f32_16x16x32_bf16 v[34:37], v[164:167], v[184:187], v[34:37]
	s_waitcnt lgkmcnt(1)
	v_mfma_f32_16x16x32_bf16 v[30:33], v[148:151], v[168:171], v[30:33]
	global_load_lds_dwordx4 v183, s[100:101]
	v_mfma_f32_16x16x32_bf16 v[26:29], v[152:155], v[168:171], v[26:29]
	v_mfma_f32_16x16x32_bf16 v[22:25], v[156:159], v[168:171], v[22:25]
	v_mfma_f32_16x16x32_bf16 v[18:21], v[164:167], v[168:171], v[18:21]
	s_waitcnt lgkmcnt(0)
	v_mfma_f32_16x16x32_bf16 v[14:17], v[148:151], v[172:175], v[14:17]
	v_mfma_f32_16x16x32_bf16 v[10:13], v[152:155], v[172:175], v[10:13]
	v_mfma_f32_16x16x32_bf16 v[6:9], v[156:159], v[172:175], v[6:9]
	v_mfma_f32_16x16x32_bf16 v[2:5], v[164:167], v[172:175], v[2:5]
	v_add_u32_e32 v160, v190, v143
	v_add_u32_e32 v161, v163, v143
	ds_read_b128 v[148:151], v160 offset:32768
	ds_read_b128 v[168:171], v161
	ds_read_b128 v[152:155], v160 offset:34816
	ds_read_b128 v[156:159], v160 offset:36864
	ds_read_b128 v[164:167], v160 offset:38912
	ds_read_b128 v[172:175], v161 offset:2048
	ds_read_b128 v[184:187], v161 offset:4096
	s_waitcnt lgkmcnt(5)
	v_mfma_f32_16x16x32_bf16 v[126:129], v[148:151], v[168:171], v[126:129]
	s_add_u32 s100, s100, 0x80
	s_waitcnt lgkmcnt(4)
	v_mfma_f32_16x16x32_bf16 v[122:125], v[152:155], v[168:171], v[122:125]
	s_addc_u32 s101, s101, 0
	s_waitcnt lgkmcnt(3)
	v_mfma_f32_16x16x32_bf16 v[118:121], v[156:159], v[168:171], v[118:121]
	s_add_u32 s2, s2, 0x80
	s_waitcnt lgkmcnt(2)
	v_mfma_f32_16x16x32_bf16 v[114:117], v[164:167], v[168:171], v[114:117]
	ds_read_b128 v[168:171], v161 offset:6144
	s_waitcnt lgkmcnt(2)
	v_mfma_f32_16x16x32_bf16 v[110:113], v[148:151], v[172:175], v[110:113]
	s_addc_u32 s3, s3, 0
	v_mfma_f32_16x16x32_bf16 v[106:109], v[152:155], v[172:175], v[106:109]
	s_add_i32 s5, s5, 0x10000
	v_mfma_f32_16x16x32_bf16 v[102:105], v[156:159], v[172:175], v[102:105]
	v_mfma_f32_16x16x32_bf16 v[98:101], v[164:167], v[172:175], v[98:101]
	ds_read_b128 v[172:175], v161 offset:8192
	s_waitcnt lgkmcnt(2)
	v_mfma_f32_16x16x32_bf16 v[94:97], v[148:151], v[184:187], v[94:97]
	v_mfma_f32_16x16x32_bf16 v[90:93], v[152:155], v[184:187], v[90:93]
	v_mfma_f32_16x16x32_bf16 v[86:89], v[156:159], v[184:187], v[86:89]
	v_mfma_f32_16x16x32_bf16 v[82:85], v[164:167], v[184:187], v[82:85]
	ds_read_b128 v[184:187], v161 offset:10240
	s_waitcnt lgkmcnt(2)
	v_mfma_f32_16x16x32_bf16 v[78:81], v[148:151], v[168:171], v[78:81]
	v_mfma_f32_16x16x32_bf16 v[74:77], v[152:155], v[168:171], v[74:77]
	v_mfma_f32_16x16x32_bf16 v[70:73], v[156:159], v[168:171], v[70:73]
	v_mfma_f32_16x16x32_bf16 v[66:69], v[164:167], v[168:171], v[66:69]
	ds_read_b128 v[168:171], v161 offset:12288
	s_waitcnt lgkmcnt(2)
	v_mfma_f32_16x16x32_bf16 v[62:65], v[148:151], v[172:175], v[62:65]
	v_mfma_f32_16x16x32_bf16 v[58:61], v[152:155], v[172:175], v[58:61]
	v_mfma_f32_16x16x32_bf16 v[54:57], v[156:159], v[172:175], v[54:57]
	v_mfma_f32_16x16x32_bf16 v[50:53], v[164:167], v[172:175], v[50:53]
	ds_read_b128 v[172:175], v161 offset:14336
	s_waitcnt lgkmcnt(2)
	v_mfma_f32_16x16x32_bf16 v[46:49], v[148:151], v[184:187], v[46:49]
	v_mfma_f32_16x16x32_bf16 v[42:45], v[152:155], v[184:187], v[42:45]
	v_mfma_f32_16x16x32_bf16 v[38:41], v[156:159], v[184:187], v[38:41]
	v_mfma_f32_16x16x32_bf16 v[34:37], v[164:167], v[184:187], v[34:37]
	s_waitcnt lgkmcnt(1)
	v_mfma_f32_16x16x32_bf16 v[30:33], v[148:151], v[168:171], v[30:33]
	v_mfma_f32_16x16x32_bf16 v[26:29], v[152:155], v[168:171], v[26:29]
	v_mfma_f32_16x16x32_bf16 v[22:25], v[156:159], v[168:171], v[22:25]
	v_mfma_f32_16x16x32_bf16 v[18:21], v[164:167], v[168:171], v[18:21]
	s_waitcnt lgkmcnt(0)
	v_mfma_f32_16x16x32_bf16 v[14:17], v[148:151], v[172:175], v[14:17]
	v_mfma_f32_16x16x32_bf16 v[10:13], v[152:155], v[172:175], v[10:13]
	v_mfma_f32_16x16x32_bf16 v[6:9], v[156:159], v[172:175], v[6:9]
	v_mfma_f32_16x16x32_bf16 v[2:5], v[164:167], v[172:175], v[2:5]
	s_cmpk_eq_i32 s2, 0x780
	s_waitcnt vmcnt(0)
	s_barrier
; #define MFMA16(a, b, c) __builtin_amdgcn_mfma_f32_16x16x32_bf16((a), (b), (c), 0, 0, 0)
;     ...
;   for (int kt = 0; kt < nk; ++kt) {
;     const int buf = kt & 1;
;     const char* cA = smem + buf * STAGE + (wm * 32 * MI + r16) * 128;
;     const char* cB = smem + buf * STAGE + 32768 + (wn * 64 + r16) * 128;
; #pragma unroll
;     for (int k2 = 0; k2 < 2; ++k2) {
;       if (k2 == 1 && kt + 1 < nk) STAGE_TILE(buf ^ 1, (kt + 1) * 64)
;       const int po = ((4 * k2 + q4) ^ swz) * 16;
;       bf16x8 bf[4];
; #pragma unroll
;       for (int nt = 0; nt < 4; ++nt) bf[nt] = *(const bf16x8*)(cB + nt * 16 * 128 + po);
;       bf16x8 afc = *(const bf16x8*)(cA + po);
; #pragma unroll
;       for (int a = 0; a < MT; ++a) {
;         bf16x8 afn = afc;
;         if (a + 1 < MT) afn = *(const bf16x8*)(cA + (a + 1) * 16 * 128 + po);
;         __builtin_amdgcn_sched_barrier(0);
; #pragma unroll
;         for (int nt = 0; nt < 4; ++nt) acc[a][nt] = MFMA16(bf[nt], afc, acc[a][nt]);
;         __builtin_amdgcn_sched_barrier(0);
;         afc = afn;
;       }
;     }
;     asm volatile("s_waitcnt vmcnt(0)" ::: "memory");
;     __syncthreads();
;   }
; DI void phase_win(char* smem, const Params& p, int layer) {
;     ...
;   auto ep = [&](int row, int cbw, int q4, const f32x4& c0, const f32x4& c1, const f32x4& c2, const f32x4& c3) {
;     if (cbw > 2432) return;
	s_cbranch_scc0 .LBB0_565
	s_add_i32 s2, 0, 0x10000
	v_add_u32_e32 v138, s2, v147
	v_readlane_b32 s2, v254, 18
	s_nop 1
	v_add_u32_e32 v139, s2, v146
	v_add_u32_e32 v144, v139, v145
	ds_read_b128 v[130:133], v144
	ds_read_b128 v[134:137], v144 offset:2048
	ds_read_b128 v[146:149], v144 offset:4096
	ds_read_b128 v[150:153], v144 offset:6144
	v_add_u32_e32 v144, v138, v145
	ds_read_b128 v[154:157], v144
	ds_read_b128 v[158:161], v144 offset:2048
	s_waitcnt lgkmcnt(1)
	v_mfma_f32_16x16x32_bf16 v[122:125], v[134:137], v[154:157], v[122:125]
	v_mfma_f32_16x16x32_bf16 v[118:121], v[146:149], v[154:157], v[118:121]
	v_mfma_f32_16x16x32_bf16 v[114:117], v[150:153], v[154:157], v[114:117]
	v_mfma_f32_16x16x32_bf16 v[126:129], v[130:133], v[154:157], v[126:129]
	ds_read_b128 v[154:157], v144 offset:4096
	s_waitcnt lgkmcnt(1)
	v_mfma_f32_16x16x32_bf16 v[110:113], v[130:133], v[158:161], v[110:113]
	v_mfma_f32_16x16x32_bf16 v[106:109], v[134:137], v[158:161], v[106:109]
	v_mfma_f32_16x16x32_bf16 v[102:105], v[146:149], v[158:161], v[102:105]
	v_mfma_f32_16x16x32_bf16 v[98:101], v[150:153], v[158:161], v[98:101]
	ds_read_b128 v[158:161], v144 offset:6144
	s_waitcnt lgkmcnt(1)
	v_mfma_f32_16x16x32_bf16 v[94:97], v[130:133], v[154:157], v[94:97]
	v_mfma_f32_16x16x32_bf16 v[90:93], v[134:137], v[154:157], v[90:93]
	v_mfma_f32_16x16x32_bf16 v[86:89], v[146:149], v[154:157], v[86:89]
	v_mfma_f32_16x16x32_bf16 v[82:85], v[150:153], v[154:157], v[82:85]
	ds_read_b128 v[154:157], v144 offset:8192
	s_waitcnt lgkmcnt(1)
	v_mfma_f32_16x16x32_bf16 v[78:81], v[130:133], v[158:161], v[78:81]
	v_mfma_f32_16x16x32_bf16 v[74:77], v[134:137], v[158:161], v[74:77]
	v_mfma_f32_16x16x32_bf16 v[70:73], v[146:149], v[158:161], v[70:73]
	v_mfma_f32_16x16x32_bf16 v[66:69], v[150:153], v[158:161], v[66:69]
	ds_read_b128 v[158:161], v144 offset:10240
	s_waitcnt lgkmcnt(1)
	v_mfma_f32_16x16x32_bf16 v[62:65], v[130:133], v[154:157], v[62:65]
	v_mfma_f32_16x16x32_bf16 v[58:61], v[134:137], v[154:157], v[58:61]
	v_mfma_f32_16x16x32_bf16 v[54:57], v[146:149], v[154:157], v[54:57]
	v_mfma_f32_16x16x32_bf16 v[50:53], v[150:153], v[154:157], v[50:53]
	ds_read_b128 v[154:157], v144 offset:12288
	s_waitcnt lgkmcnt(1)
	v_mfma_f32_16x16x32_bf16 v[46:49], v[130:133], v[158:161], v[46:49]
	v_mfma_f32_16x16x32_bf16 v[42:45], v[134:137], v[158:161], v[42:45]
	v_mfma_f32_16x16x32_bf16 v[38:41], v[146:149], v[158:161], v[38:41]
	v_mfma_f32_16x16x32_bf16 v[34:37], v[150:153], v[158:161], v[34:37]
	ds_read_b128 v[158:161], v144 offset:14336
	s_waitcnt lgkmcnt(1)
	v_mfma_f32_16x16x32_bf16 v[30:33], v[130:133], v[154:157], v[30:33]
	v_mfma_f32_16x16x32_bf16 v[26:29], v[134:137], v[154:157], v[26:29]
	v_mfma_f32_16x16x32_bf16 v[22:25], v[146:149], v[154:157], v[22:25]
	v_mfma_f32_16x16x32_bf16 v[18:21], v[150:153], v[154:157], v[18:21]
	s_waitcnt lgkmcnt(0)
	v_mfma_f32_16x16x32_bf16 v[14:17], v[130:133], v[158:161], v[14:17]
	v_mfma_f32_16x16x32_bf16 v[10:13], v[134:137], v[158:161], v[10:13]
	v_mfma_f32_16x16x32_bf16 v[6:9], v[146:149], v[158:161], v[6:9]
	v_mfma_f32_16x16x32_bf16 v[2:5], v[150:153], v[158:161], v[2:5]
	v_add_u32_e32 v130, v139, v143
	ds_read_b128 v[134:137], v130
	ds_read_b128 v[144:147], v130 offset:2048
	ds_read_b128 v[148:151], v130 offset:4096
	ds_read_b128 v[152:155], v130 offset:6144
	v_add_u32_e32 v138, v138, v143
	ds_read_b128 v[156:159], v138
	ds_read_b128 v[164:167], v138 offset:2048
	s_waitcnt lgkmcnt(1)
	v_mfma_f32_16x16x32_bf16 v[130:133], v[134:137], v[156:159], v[126:129]
	v_mfma_f32_16x16x32_bf16 v[122:125], v[144:147], v[156:159], v[122:125]
	v_mfma_f32_16x16x32_bf16 v[118:121], v[148:151], v[156:159], v[118:121]
	v_mfma_f32_16x16x32_bf16 v[114:117], v[152:155], v[156:159], v[114:117]
	ds_read_b128 v[126:129], v138 offset:4096
	s_waitcnt lgkmcnt(1)
	v_mfma_f32_16x16x32_bf16 v[110:113], v[134:137], v[164:167], v[110:113]
	v_mfma_f32_16x16x32_bf16 v[106:109], v[144:147], v[164:167], v[106:109]
	v_mfma_f32_16x16x32_bf16 v[102:105], v[148:151], v[164:167], v[102:105]
	v_mfma_f32_16x16x32_bf16 v[98:101], v[152:155], v[164:167], v[98:101]
	ds_read_b128 v[156:159], v138 offset:6144
	s_waitcnt lgkmcnt(1)
	v_mfma_f32_16x16x32_bf16 v[94:97], v[134:137], v[126:129], v[94:97]
	v_mfma_f32_16x16x32_bf16 v[90:93], v[144:147], v[126:129], v[90:93]
	v_mfma_f32_16x16x32_bf16 v[86:89], v[148:151], v[126:129], v[86:89]
	v_mfma_f32_16x16x32_bf16 v[82:85], v[152:155], v[126:129], v[82:85]
	ds_read_b128 v[126:129], v138 offset:8192
	s_waitcnt lgkmcnt(1)
	v_mfma_f32_16x16x32_bf16 v[78:81], v[134:137], v[156:159], v[78:81]
	v_mfma_f32_16x16x32_bf16 v[74:77], v[144:147], v[156:159], v[74:77]
	v_mfma_f32_16x16x32_bf16 v[70:73], v[148:151], v[156:159], v[70:73]
	v_mfma_f32_16x16x32_bf16 v[66:69], v[152:155], v[156:159], v[66:69]
	ds_read_b128 v[156:159], v138 offset:10240
	s_waitcnt lgkmcnt(1)
	v_mfma_f32_16x16x32_bf16 v[62:65], v[134:137], v[126:129], v[62:65]
	v_mfma_f32_16x16x32_bf16 v[58:61], v[144:147], v[126:129], v[58:61]
	v_mfma_f32_16x16x32_bf16 v[54:57], v[148:151], v[126:129], v[54:57]
	v_mfma_f32_16x16x32_bf16 v[50:53], v[152:155], v[126:129], v[50:53]
	ds_read_b128 v[126:129], v138 offset:12288
	s_waitcnt lgkmcnt(1)
	v_mfma_f32_16x16x32_bf16 v[46:49], v[134:137], v[156:159], v[46:49]
	v_mfma_f32_16x16x32_bf16 v[42:45], v[144:147], v[156:159], v[42:45]
	v_mfma_f32_16x16x32_bf16 v[38:41], v[148:151], v[156:159], v[38:41]
	v_mfma_f32_16x16x32_bf16 v[34:37], v[152:155], v[156:159], v[34:37]
	ds_read_b128 v[156:159], v138 offset:14336
	s_waitcnt lgkmcnt(1)
	v_mfma_f32_16x16x32_bf16 v[30:33], v[134:137], v[126:129], v[30:33]
	v_mfma_f32_16x16x32_bf16 v[26:29], v[144:147], v[126:129], v[26:29]
	v_mfma_f32_16x16x32_bf16 v[22:25], v[148:151], v[126:129], v[22:25]
	v_mfma_f32_16x16x32_bf16 v[18:21], v[152:155], v[126:129], v[18:21]
	s_waitcnt lgkmcnt(0)
	v_mfma_f32_16x16x32_bf16 v[14:17], v[134:137], v[156:159], v[14:17]
	v_mfma_f32_16x16x32_bf16 v[10:13], v[144:147], v[156:159], v[10:13]
	v_mfma_f32_16x16x32_bf16 v[6:9], v[148:151], v[156:159], v[6:9]
	v_mfma_f32_16x16x32_bf16 v[2:5], v[152:155], v[156:159], v[2:5]
	s_waitcnt vmcnt(0)
	v_lshl_or_b32 v190, v142, 6, s22
	s_movk_i32 s2, 0x981
	v_cmp_gt_i32_e32 vcc, s2, v190
	s_barrier
; DI bf16_t f2bf(float x) { return (bf16_t)(pack2(x, 0.f) & 0xffffu); }
; DI void phase_win(char* smem, const Params& p, int layer) {
;     ...
;   auto ep = [&](int row, int cbw, int q4, const f32x4& c0, const f32x4& c1, const f32x4& c2, const f32x4& c3) {
;     if (cbw > 2432) return;
;     const int b = row / TT, t = row - b * TT;
;     const bool lat = t >= CTXL;
;     const int pos = t - CTXL;
;     float v[16] = {c0[0], c0[1], c0[2], c0[3], c1[0], c1[1], c1[2], c1[3], c2[0], c2[1], c2[2], c2[3], c3[0], c3[1], c3[2], c3[3]};
;     if (cbw >= 640 && cbw < 768) {
;       bf16_t* vp = p.VsT + ((size_t)(b * 2 + ((cbw - 640) >> 6)) * 64 + q4 * 16) * TT + t;
; #pragma unroll
;       for (int i = 0; i < 16; ++i) vp[(size_t)i * TT] = f2bf(v[i]);
;       return;
;     }
;     const bool r16 = cbw >= 256 && cbw < 640, rkr = cbw == 2432;
;     if (rkr && q4 >= 2) return;
;     if (lat && (r16 || rkr)) {
;       const int a = r16 ? (q4 >> 1) : q4;
;       const int pa = a ? (pos & 63) : (pos >> 6);
;       const float* tab = r16 ? p.ropeS + 2 * (pa * 16 + (q4 & 1) * 8) : p.ropeM + 2 * (pa * 8);
; #pragma unroll
;       for (int k = 0; k < 4; ++k) {
;         const float4 cs = *(const float4*)(tab + 4 * k);
;         const float x0 = v[4 * k], x1 = v[4 * k + 1], x2 = v[4 * k + 2], x3 = v[4 * k + 3];
;         v[4 * k] = x0 * cs.x - x1 * cs.y; v[4 * k + 1] = x1 * cs.x + x0 * cs.y;
;         v[4 * k + 2] = x2 * cs.z - x3 * cs.w; v[4 * k + 3] = x3 * cs.z + x2 * cs.w;
;       }
	s_and_saveexec_b64 s[96:97], vcc
	s_cbranch_execz .LBB0_557
	v_or_b32_e32 v126, s4, v162
	v_lshl_add_u32 v136, v141, 7, v126
	v_and_b32_e32 v126, 0xffffff80, v190
	s_movk_i32 s2, 0x280
	v_cmp_ne_u32_e64 s[16:17], s2, v126
	s_movk_i32 s2, 0x27f
	v_cmp_lt_i32_e64 s[4:5], s2, v190
	s_movk_i32 s2, 0x980
	v_cmp_ne_u32_e64 s[8:9], s2, v190
	v_cmp_gt_u32_e64 s[6:7], 2, v140
	v_add_u32_e32 v126, 0xffffff00, v190
	v_cmp_eq_u32_e32 vcc, s2, v190
	s_or_b64 s[2:3], s[8:9], s[6:7]
	s_movk_i32 s6, 0x180
	v_cmp_gt_u32_e64 s[12:13], s6, v126
	s_or_b64 s[86:87], vcc, s[12:13]
	v_lshrrev_b32_e32 v160, 6, v126
	v_cndmask_b32_e64 v127, 0, 1, s[12:13]
	v_lshrrev_b32_e32 v127, v127, v140
	v_cmp_eq_u32_e64 s[14:15], 0, v127
	v_add_u32_e32 v127, 0xfffffe00, v190
	v_mul_hi_i32 v126, v136, s1
	s_cmp_eq_u32 s10, 1
	v_lshrrev_b32_e32 v159, 6, v127
	v_lshrrev_b32_e32 v127, 31, v126
	v_ashrrev_i32_e32 v126, 11, v126
	v_lshlrev_b32_e32 v158, 4, v140
	s_movk_i32 s6, 0x1ff
	s_cselect_b64 s[94:95], -1, 0
	s_movk_i32 s10, 0xff
	s_cmpk_gt_u32 s22, 0x7ff
	v_add_u32_e32 v139, v126, v127
	v_and_b32_e32 v161, 16, v158
	v_cmp_lt_i32_e64 s[6:7], s6, v190
	v_cmp_lt_i32_e64 s[10:11], s10, v190
	s_cselect_b64 s[22:23], -1, 0
	v_ashrrev_i32_e32 v135, 31, v190
	v_mov_b32_e32 v134, v190
	v_mad_i32_i24 v138, v139, s80, v136
	s_and_saveexec_b64 s[30:31], s[16:17]
	s_xor_b64 s[30:31], exec, s[30:31]
	s_cbranch_execz .LBB0_594
	s_and_saveexec_b64 s[52:53], s[2:3]
	s_cbranch_execz .LBB0_593
	s_movk_i32 s45, 0xff
	v_cmp_lt_i32_e32 vcc, s45, v138
	s_and_b64 s[46:47], s[86:87], vcc
	v_mov_b32_e32 v140, v131
	v_mov_b32_e32 v141, v133
	v_mov_b32_e32 v142, v123
	v_mov_b32_e32 v143, v125
	v_mov_b32_e32 v144, v119
	v_mov_b32_e32 v145, v121
	v_mov_b32_e32 v154, v115
	v_mov_b32_e32 v155, v117
	v_mov_b32_e32 v146, v130
	v_mov_b32_e32 v147, v132
	v_mov_b32_e32 v148, v122
	v_mov_b32_e32 v149, v124
	v_mov_b32_e32 v150, v118
	v_mov_b32_e32 v151, v120
	v_mov_b32_e32 v152, v114
	v_mov_b32_e32 v153, v116
	s_and_saveexec_b64 s[54:55], s[46:47]
	s_cbranch_execz .LBB0_571
	v_readlane_b32 s46, v252, 1
	v_cndmask_b32_e64 v128, v238, v240, s[12:13]
	v_mov_b32_e32 v129, v191
	v_readlane_b32 s47, v252, 2
	v_add_u32_e32 v126, 0xffffff00, v138
	v_lshrrev_b32_e32 v126, 6, v126
	v_lshl_add_u64 v[128:129], s[46:47], 0, v[128:129]
	global_load_dwordx2 v[128:129], v[128:129], off
	v_cndmask_b32_e64 v126, v162, v126, s[14:15]
	v_lshlrev_b32_e32 v127, 4, v126
	v_lshl_or_b32 v126, v126, 5, v161
	v_cndmask_b32_e64 v126, v127, v126, s[12:13]
	v_mov_b32_e32 v127, v191
	v_mov_b32_e32 v182, v130
	v_mov_b32_e32 v183, v133
	v_mov_b32_e32 v130, v131
	v_mov_b32_e32 v131, v132
	s_waitcnt vmcnt(0)
	v_lshl_add_u64 v[156:157], v[126:127], 2, v[128:129]
	global_load_dwordx4 v[126:129], v[156:157], off offset:48
	global_load_dwordx4 v[164:167], v[156:157], off offset:32
	global_load_dwordx4 v[168:171], v[156:157], off offset:16
	global_load_dwordx4 v[172:175], v[156:157], off
	s_waitcnt vmcnt(3)
	v_mov_b32_e32 v156, v127
	s_waitcnt vmcnt(2)
	v_mov_b32_e32 v180, v165
	s_waitcnt vmcnt(1)
	v_mov_b32_e32 v178, v169
	s_waitcnt vmcnt(0)
	v_mov_b32_e32 v132, v172
	v_mov_b32_e32 v133, v175
	v_mov_b32_e32 v176, v173
	v_mov_b32_e32 v177, v174
	v_pk_mul_f32 v[130:131], v[130:131], v[132:133]
	v_mov_b32_e32 v132, v173
	v_pk_mul_f32 v[132:133], v[140:141], v[132:133]
	v_pk_fma_f32 v[140:141], v[182:183], v[176:177], v[130:131]
	v_mov_b32_e32 v130, v122
	v_mov_b32_e32 v131, v125
	v_mov_b32_e32 v122, v123
	v_mov_b32_e32 v123, v124
	v_mov_b32_e32 v124, v168
	v_mov_b32_e32 v125, v171
	v_mov_b32_e32 v179, v170
	v_pk_mul_f32 v[122:123], v[122:123], v[124:125]
	v_mov_b32_e32 v124, v169
	v_pk_mul_f32 v[124:125], v[142:143], v[124:125]
	v_pk_fma_f32 v[142:143], v[130:131], v[178:179], v[122:123]
	v_mov_b32_e32 v122, v118
	v_mov_b32_e32 v123, v121
	v_mov_b32_e32 v118, v119
	v_mov_b32_e32 v119, v120
	v_mov_b32_e32 v120, v164
	v_mov_b32_e32 v121, v167
	v_mov_b32_e32 v181, v166
	v_pk_mul_f32 v[118:119], v[118:119], v[120:121]
	v_mov_b32_e32 v120, v165
	v_pk_mul_f32 v[120:121], v[144:145], v[120:121]
	v_pk_fma_f32 v[144:145], v[122:123], v[180:181], v[118:119]
	v_mov_b32_e32 v118, v114
	v_mov_b32_e32 v119, v117
	v_mov_b32_e32 v114, v115
	v_mov_b32_e32 v115, v116
	v_mov_b32_e32 v116, v126
	v_mov_b32_e32 v117, v129
	v_pk_mul_f32 v[114:115], v[114:115], v[116:117]
	v_mov_b32_e32 v116, v127
	v_mov_b32_e32 v157, v128
	v_mov_b32_e32 v173, v174
	v_mov_b32_e32 v169, v170
	v_mov_b32_e32 v165, v166
	v_pk_mul_f32 v[116:117], v[154:155], v[116:117]
	v_mov_b32_e32 v127, v128
	v_pk_fma_f32 v[146:147], v[146:147], v[172:173], v[132:133] neg_lo:[0,0,1] neg_hi:[0,0,1]
	v_pk_fma_f32 v[148:149], v[148:149], v[168:169], v[124:125] neg_lo:[0,0,1] neg_hi:[0,0,1]
	v_pk_fma_f32 v[150:151], v[150:151], v[164:165], v[120:121] neg_lo:[0,0,1] neg_hi:[0,0,1]
	v_pk_fma_f32 v[152:153], v[152:153], v[126:127], v[116:117] neg_lo:[0,0,1] neg_hi:[0,0,1]
	v_pk_fma_f32 v[154:155], v[118:119], v[156:157], v[114:115]
